# on top of the hgB scan pipelining: ada_partials k-loop fully unrolled with a two-iterations-ahead prefetch (counted vmcnt), and norm_rows issues all gain/scale/shift chunk loads with the row loads ins
# speedup vs baseline: 1.0135x; 1.0029x over previous
; DI void ada_partials(const P& p, LAS unsigned char* L) {
;     ...
;     for (int item = blockIdx.x; item < 768; item += gridDim.x) {
;         const int l = item / 384, r = item % 384, cb = r / 16, ks = r % 16;
;         __syncthreads();
;         { const int b = tid >> 7, k = tid & 127; const float cv = p.c[b * DM + ks * 128 + k]; condl[tid] = cv * __builtin_amdgcn_rcpf(1.f + __expf(-cv)); }
;         __syncthreads();
;         const int col = cb * 512 + tid;
;         const float* w = p.ada_w + ((size_t)l * DM + ks * 128) * MODW + col;
;         float a0 = 0.f, a1 = 0.f, a2 = 0.f, a3 = 0.f;
; #pragma unroll 8
;         for (int k = 0; k < 128; ++k) { const float wv = w[(size_t)k * MODW]; a0 += condl[k] * wv; a1 += condl[128 + k] * wv; a2 += condl[256 + k] * wv; a3 += condl[384 + k] * wv; }
.LBB0_46:
	s_mul_hi_i32 s4, s19, 0x2aaaaaab
	s_lshr_b32 s5, s4, 31
	s_ashr_i32 s20, s4, 6
	s_add_i32 s20, s20, s5
	s_mul_i32 s4, s20, 0x180
	s_sub_i32 s4, s19, s4
	s_bfe_u32 s5, s4, 0x4001b
	s_add_i32 s5, s4, s5
	s_and_b32 s21, s5, 0xfff0
	s_sub_i32 s4, s4, s21
	s_sext_i32_i16 s21, s4
	s_lshl_b32 s4, s21, 7
	v_add_u32_e32 v0, s4, v9
	v_ashrrev_i32_e32 v1, 31, v0
	v_lshl_add_u64 v[0:1], v[0:1], 2, s[8:9]
	s_barrier
	global_load_dword v5, v[0:1], off
	s_sext_i32_i16 s5, s5
	s_lshl_b32 s5, s5, 5
	s_and_b32 s5, s5, 0xfffffe00
	s_mul_i32 s24, s20, 0x6000000
	v_add_u32_e32 v2, s5, v8
	s_mul_i32 s5, s21, 0x600000
	s_mul_hi_i32 s23, s20, 0x6000000
	s_mul_hi_i32 s4, s4, 0xc000
	s_add_u32 s5, s24, s5
	s_addc_u32 s23, s23, s4
	s_add_u32 s4, s3, s5
	v_mov_b32_e32 v0, 0
	v_ashrrev_i32_e32 v3, 31, v2
	s_addc_u32 s5, s12, s23
	s_movk_i32 s22, 0xfe00
	v_mov_b32_e32 v1, v0
	v_mov_b32_e32 v4, v0
	s_waitcnt vmcnt(0)
	v_mul_f32_e32 v6, 0xbfb8aa3b, v5
	v_exp_f32_e32 v6, v6
	s_nop 0
	v_add_f32_e32 v6, 1.0, v6
	v_rcp_f32_e32 v11, v6
	v_lshl_add_u64 v[6:7], v[2:3], 2, s[4:5]
	v_mul_f32_e32 v5, v5, v11
	ds_write_b32 v10, v5
	v_mov_b32_e32 v5, v0
	s_waitcnt lgkmcnt(0)
	s_barrier
	v_mov_b32_e32 v11, 0x20000
	v_add_co_u32_e64 v14, s[4:5], s14, v6
	v_add_co_u32_e32 v12, vcc, 0xfffd0000, v6
	s_nop 0
	v_addc_co_u32_e64 v15, s[4:5], -1, v7, s[4:5]
	v_add_co_u32_e64 v16, s[4:5], s15, v6
	global_load_dword v44, v[6:7], off
	s_nop 0
	v_addc_co_u32_e64 v17, s[4:5], -1, v7, s[4:5]
	v_add_co_u32_e64 v18, s[4:5], s16, v6
	v_addc_co_u32_e32 v13, vcc, -1, v7, vcc
	s_nop 0
	v_addc_co_u32_e64 v19, s[4:5], -1, v7, s[4:5]
	v_add_co_u32_e64 v20, s[4:5], s13, v6
	s_nop 1
	v_addc_co_u32_e64 v21, s[4:5], 0, v7, s[4:5]
	v_add_co_u32_e64 v22, s[4:5], s17, v6
	s_nop 1
	v_addc_co_u32_e64 v23, s[4:5], 0, v7, s[4:5]
	v_add_co_u32_e64 v24, s[4:5], s18, v6
	s_nop 1
	v_addc_co_u32_e64 v25, s[4:5], 0, v7, s[4:5]
	global_load_dword v46, v[14:15], off
	global_load_dword v48, v[16:17], off
	global_load_dword v50, v[12:13], off
	global_load_dword v52, v[18:19], off
	global_load_dword v54, v[20:21], off
	global_load_dword v56, v[22:23], off
	global_load_dword v58, v[24:25], off
	v_lshl_add_u64 v[6:7], v[6:7], 0, s[10:11]
	v_add_co_u32_e64 v14, s[4:5], s14, v6
	v_add_co_u32_e32 v12, vcc, 0xfffd0000, v6
	s_nop 0
	v_addc_co_u32_e64 v15, s[4:5], -1, v7, s[4:5]
	v_add_co_u32_e64 v16, s[4:5], s15, v6
	global_load_dword v64, v[6:7], off
	s_nop 0
	v_addc_co_u32_e64 v17, s[4:5], -1, v7, s[4:5]
	v_add_co_u32_e64 v18, s[4:5], s16, v6
	v_addc_co_u32_e32 v13, vcc, -1, v7, vcc
	s_nop 0
	v_addc_co_u32_e64 v19, s[4:5], -1, v7, s[4:5]
	v_add_co_u32_e64 v20, s[4:5], s13, v6
	s_nop 1
	v_addc_co_u32_e64 v21, s[4:5], 0, v7, s[4:5]
	v_add_co_u32_e64 v22, s[4:5], s17, v6
	s_nop 1
	v_addc_co_u32_e64 v23, s[4:5], 0, v7, s[4:5]
	v_add_co_u32_e64 v24, s[4:5], s18, v6
	s_nop 1
	v_addc_co_u32_e64 v25, s[4:5], 0, v7, s[4:5]
	global_load_dword v66, v[14:15], off
	global_load_dword v68, v[16:17], off
	global_load_dword v70, v[12:13], off
	global_load_dword v72, v[18:19], off
	global_load_dword v74, v[20:21], off
	global_load_dword v76, v[22:23], off
	global_load_dword v78, v[24:25], off
	v_lshl_add_u64 v[6:7], v[6:7], 0, s[10:11]
	v_add_co_u32_e64 v14, s[4:5], s14, v6
	v_add_co_u32_e32 v12, vcc, 0xfffd0000, v6
	s_nop 0
	v_addc_co_u32_e64 v15, s[4:5], -1, v7, s[4:5]
	v_add_co_u32_e64 v16, s[4:5], s15, v6
	global_load_dword v80, v[6:7], off
	s_nop 0
	v_addc_co_u32_e64 v17, s[4:5], -1, v7, s[4:5]
	v_add_co_u32_e64 v18, s[4:5], s16, v6
	v_addc_co_u32_e32 v13, vcc, -1, v7, vcc
	s_nop 0
	v_addc_co_u32_e64 v19, s[4:5], -1, v7, s[4:5]
	v_add_co_u32_e64 v20, s[4:5], s13, v6
	s_nop 1
	v_addc_co_u32_e64 v21, s[4:5], 0, v7, s[4:5]
	v_add_co_u32_e64 v22, s[4:5], s17, v6
	s_nop 1
	v_addc_co_u32_e64 v23, s[4:5], 0, v7, s[4:5]
	v_add_co_u32_e64 v24, s[4:5], s18, v6
	s_nop 1
	v_addc_co_u32_e64 v25, s[4:5], 0, v7, s[4:5]
	global_load_dword v82, v[14:15], off
	global_load_dword v84, v[16:17], off
	global_load_dword v86, v[12:13], off
	global_load_dword v88, v[18:19], off
	global_load_dword v90, v[20:21], off
	global_load_dword v92, v[22:23], off
	global_load_dword v94, v[24:25], off
	v_lshl_add_u64 v[6:7], v[6:7], 0, s[10:11]
	ds_read_b128 v[12:15], v11 offset:0
	ds_read_b128 v[16:19], v11 offset:512
	ds_read_b128 v[20:23], v11 offset:1024
	ds_read_b128 v[24:27], v11 offset:1536
	ds_read_b128 v[28:31], v11 offset:16
	ds_read_b128 v[32:35], v11 offset:528
	ds_read_b128 v[36:39], v11 offset:1040
	ds_read_b128 v[40:43], v11 offset:1552
	s_waitcnt lgkmcnt(6)
	v_mov_b32_e32 v60, v16
	v_mov_b32_e32 v61, v12
	s_waitcnt lgkmcnt(4)
	v_mov_b32_e32 v62, v24
	v_mov_b32_e32 v63, v20
	v_mov_b32_e32 v12, v17
	v_mov_b32_e32 v20, v25
	v_mov_b32_e32 v16, v18
	v_mov_b32_e32 v17, v14
	v_mov_b32_e32 v14, v19
	v_mov_b32_e32 v18, v26
	v_mov_b32_e32 v19, v22
	v_mov_b32_e32 v22, v27
	s_waitcnt lgkmcnt(2)
	v_mov_b32_e32 v24, v32
	v_mov_b32_e32 v25, v28
	s_waitcnt lgkmcnt(0)
	v_mov_b32_e32 v26, v40
	v_mov_b32_e32 v27, v36
	v_mov_b32_e32 v28, v33
	v_mov_b32_e32 v36, v41
	v_mov_b32_e32 v32, v34
	v_mov_b32_e32 v33, v30
	v_mov_b32_e32 v30, v35
	v_mov_b32_e32 v34, v42
	v_mov_b32_e32 v35, v38
	v_mov_b32_e32 v38, v43
	s_waitcnt vmcnt(20)
	v_pk_fma_f32 v[4:5], v[50:51], v[60:61], v[4:5] op_sel_hi:[0,1,1]
	v_pk_fma_f32 v[0:1], v[50:51], v[62:63], v[0:1] op_sel_hi:[0,1,1]
	v_pk_fma_f32 v[4:5], v[46:47], v[12:13], v[4:5] op_sel_hi:[0,1,1]
	v_pk_fma_f32 v[0:1], v[46:47], v[20:21], v[0:1] op_sel_hi:[0,1,1]
	v_pk_fma_f32 v[4:5], v[48:49], v[16:17], v[4:5] op_sel_hi:[0,1,1]
	v_pk_fma_f32 v[0:1], v[48:49], v[18:19], v[0:1] op_sel_hi:[0,1,1]
	s_waitcnt vmcnt(19)
; DI void ada_partials(const P& p, LAS unsigned char* L) {
;     ...
; #pragma unroll 8
;         for (int k = 0; k < 128; ++k) { const float wv = w[(size_t)k * MODW]; a0 += condl[k] * wv; a1 += condl[128 + k] * wv; a2 += condl[256 + k] * wv; a3 += condl[384 + k] * wv; }
	v_pk_fma_f32 v[4:5], v[52:53], v[14:15], v[4:5] op_sel_hi:[0,1,1]
	v_pk_fma_f32 v[0:1], v[52:53], v[22:23], v[0:1] op_sel_hi:[0,1,1]
	v_pk_fma_f32 v[4:5], v[44:45], v[24:25], v[4:5] op_sel_hi:[0,1,1]
	v_pk_fma_f32 v[0:1], v[44:45], v[26:27], v[0:1] op_sel_hi:[0,1,1]
	s_waitcnt vmcnt(18)
	v_pk_fma_f32 v[4:5], v[54:55], v[28:29], v[4:5] op_sel_hi:[0,1,1]
	v_pk_fma_f32 v[0:1], v[54:55], v[36:37], v[0:1] op_sel_hi:[0,1,1]
	s_waitcnt vmcnt(17)
	v_pk_fma_f32 v[4:5], v[56:57], v[32:33], v[4:5] op_sel_hi:[0,1,1]
	v_pk_fma_f32 v[0:1], v[56:57], v[34:35], v[0:1] op_sel_hi:[0,1,1]
	s_waitcnt vmcnt(16)
	v_pk_fma_f32 v[4:5], v[58:59], v[30:31], v[4:5] op_sel_hi:[0,1,1]
	v_pk_fma_f32 v[0:1], v[58:59], v[38:39], v[0:1] op_sel_hi:[0,1,1]
	v_add_co_u32_e64 v14, s[4:5], s14, v6
	v_add_co_u32_e32 v12, vcc, 0xfffd0000, v6
	s_nop 0
	v_addc_co_u32_e64 v15, s[4:5], -1, v7, s[4:5]
	v_add_co_u32_e64 v16, s[4:5], s15, v6
	global_load_dword v44, v[6:7], off
	s_nop 0
	v_addc_co_u32_e64 v17, s[4:5], -1, v7, s[4:5]
	v_add_co_u32_e64 v18, s[4:5], s16, v6
	v_addc_co_u32_e32 v13, vcc, -1, v7, vcc
	s_nop 0
	v_addc_co_u32_e64 v19, s[4:5], -1, v7, s[4:5]
	v_add_co_u32_e64 v20, s[4:5], s13, v6
	s_nop 1
	v_addc_co_u32_e64 v21, s[4:5], 0, v7, s[4:5]
	v_add_co_u32_e64 v22, s[4:5], s17, v6
	s_nop 1
	v_addc_co_u32_e64 v23, s[4:5], 0, v7, s[4:5]
	v_add_co_u32_e64 v24, s[4:5], s18, v6
	s_nop 1
	v_addc_co_u32_e64 v25, s[4:5], 0, v7, s[4:5]
	global_load_dword v46, v[14:15], off
	global_load_dword v48, v[16:17], off
	global_load_dword v50, v[12:13], off
	global_load_dword v52, v[18:19], off
	global_load_dword v54, v[20:21], off
	global_load_dword v56, v[22:23], off
	global_load_dword v58, v[24:25], off
	v_lshl_add_u64 v[6:7], v[6:7], 0, s[10:11]
	ds_read_b128 v[12:15], v11 offset:32
	ds_read_b128 v[16:19], v11 offset:544
	ds_read_b128 v[20:23], v11 offset:1056
	ds_read_b128 v[24:27], v11 offset:1568
	ds_read_b128 v[28:31], v11 offset:48
	ds_read_b128 v[32:35], v11 offset:560
	ds_read_b128 v[36:39], v11 offset:1072
	ds_read_b128 v[40:43], v11 offset:1584
	s_waitcnt lgkmcnt(6)
	v_mov_b32_e32 v60, v16
	v_mov_b32_e32 v61, v12
	s_waitcnt lgkmcnt(4)
	v_mov_b32_e32 v62, v24
	v_mov_b32_e32 v63, v20
	v_mov_b32_e32 v12, v17
	v_mov_b32_e32 v20, v25
	v_mov_b32_e32 v16, v18
	v_mov_b32_e32 v17, v14
	v_mov_b32_e32 v14, v19
	v_mov_b32_e32 v18, v26
	v_mov_b32_e32 v19, v22
	v_mov_b32_e32 v22, v27
	s_waitcnt lgkmcnt(2)
	v_mov_b32_e32 v24, v32
	v_mov_b32_e32 v25, v28
	s_waitcnt lgkmcnt(0)
	v_mov_b32_e32 v26, v40
	v_mov_b32_e32 v27, v36
	v_mov_b32_e32 v28, v33
	v_mov_b32_e32 v36, v41
	v_mov_b32_e32 v32, v34
	v_mov_b32_e32 v33, v30
	v_mov_b32_e32 v30, v35
	v_mov_b32_e32 v34, v42
	v_mov_b32_e32 v35, v38
	v_mov_b32_e32 v38, v43
	s_waitcnt vmcnt(20)
	v_pk_fma_f32 v[4:5], v[70:71], v[60:61], v[4:5] op_sel_hi:[0,1,1]
	v_pk_fma_f32 v[0:1], v[70:71], v[62:63], v[0:1] op_sel_hi:[0,1,1]
	v_pk_fma_f32 v[4:5], v[66:67], v[12:13], v[4:5] op_sel_hi:[0,1,1]
	v_pk_fma_f32 v[0:1], v[66:67], v[20:21], v[0:1] op_sel_hi:[0,1,1]
	v_pk_fma_f32 v[4:5], v[68:69], v[16:17], v[4:5] op_sel_hi:[0,1,1]
	v_pk_fma_f32 v[0:1], v[68:69], v[18:19], v[0:1] op_sel_hi:[0,1,1]
	s_waitcnt vmcnt(19)
	v_pk_fma_f32 v[4:5], v[72:73], v[14:15], v[4:5] op_sel_hi:[0,1,1]
	v_pk_fma_f32 v[0:1], v[72:73], v[22:23], v[0:1] op_sel_hi:[0,1,1]
	v_pk_fma_f32 v[4:5], v[64:65], v[24:25], v[4:5] op_sel_hi:[0,1,1]
	v_pk_fma_f32 v[0:1], v[64:65], v[26:27], v[0:1] op_sel_hi:[0,1,1]
	s_waitcnt vmcnt(18)
	v_pk_fma_f32 v[4:5], v[74:75], v[28:29], v[4:5] op_sel_hi:[0,1,1]
	v_pk_fma_f32 v[0:1], v[74:75], v[36:37], v[0:1] op_sel_hi:[0,1,1]
	s_waitcnt vmcnt(17)
	v_pk_fma_f32 v[4:5], v[76:77], v[32:33], v[4:5] op_sel_hi:[0,1,1]
	v_pk_fma_f32 v[0:1], v[76:77], v[34:35], v[0:1] op_sel_hi:[0,1,1]
	s_waitcnt vmcnt(16)
	v_pk_fma_f32 v[4:5], v[78:79], v[30:31], v[4:5] op_sel_hi:[0,1,1]
	v_pk_fma_f32 v[0:1], v[78:79], v[38:39], v[0:1] op_sel_hi:[0,1,1]
	v_add_co_u32_e64 v14, s[4:5], s14, v6
	v_add_co_u32_e32 v12, vcc, 0xfffd0000, v6
	s_nop 0
	v_addc_co_u32_e64 v15, s[4:5], -1, v7, s[4:5]
	v_add_co_u32_e64 v16, s[4:5], s15, v6
	global_load_dword v64, v[6:7], off
	s_nop 0
	v_addc_co_u32_e64 v17, s[4:5], -1, v7, s[4:5]
	v_add_co_u32_e64 v18, s[4:5], s16, v6
	v_addc_co_u32_e32 v13, vcc, -1, v7, vcc
	s_nop 0
	v_addc_co_u32_e64 v19, s[4:5], -1, v7, s[4:5]
	v_add_co_u32_e64 v20, s[4:5], s13, v6
	s_nop 1
	v_addc_co_u32_e64 v21, s[4:5], 0, v7, s[4:5]
	v_add_co_u32_e64 v22, s[4:5], s17, v6
	s_nop 1
	v_addc_co_u32_e64 v23, s[4:5], 0, v7, s[4:5]
	v_add_co_u32_e64 v24, s[4:5], s18, v6
	s_nop 1
	v_addc_co_u32_e64 v25, s[4:5], 0, v7, s[4:5]
	global_load_dword v66, v[14:15], off
	global_load_dword v68, v[16:17], off
	global_load_dword v70, v[12:13], off
	global_load_dword v72, v[18:19], off
	global_load_dword v74, v[20:21], off
	global_load_dword v76, v[22:23], off
	global_load_dword v78, v[24:25], off
	v_lshl_add_u64 v[6:7], v[6:7], 0, s[10:11]
	ds_read_b128 v[12:15], v11 offset:64
	ds_read_b128 v[16:19], v11 offset:576
	ds_read_b128 v[20:23], v11 offset:1088
	ds_read_b128 v[24:27], v11 offset:1600
	ds_read_b128 v[28:31], v11 offset:80
	ds_read_b128 v[32:35], v11 offset:592
	ds_read_b128 v[36:39], v11 offset:1104
	ds_read_b128 v[40:43], v11 offset:1616
	s_waitcnt lgkmcnt(6)
	v_mov_b32_e32 v60, v16
	v_mov_b32_e32 v61, v12
	s_waitcnt lgkmcnt(4)
	v_mov_b32_e32 v62, v24
	v_mov_b32_e32 v63, v20
	v_mov_b32_e32 v12, v17
	v_mov_b32_e32 v20, v25
	v_mov_b32_e32 v16, v18
	v_mov_b32_e32 v17, v14
	v_mov_b32_e32 v14, v19
	v_mov_b32_e32 v18, v26
	v_mov_b32_e32 v19, v22
	v_mov_b32_e32 v22, v27
	s_waitcnt lgkmcnt(2)
	v_mov_b32_e32 v24, v32
	v_mov_b32_e32 v25, v28
	s_waitcnt lgkmcnt(0)
; DI void ada_partials(const P& p, LAS unsigned char* L) {
;     ...
;         const int col = cb * 512 + tid;
;         const float* w = p.ada_w + ((size_t)l * DM + ks * 128) * MODW + col;
;         float a0 = 0.f, a1 = 0.f, a2 = 0.f, a3 = 0.f;
; #pragma unroll 8
;         for (int k = 0; k < 128; ++k) { const float wv = w[(size_t)k * MODW]; a0 += condl[k] * wv; a1 += condl[128 + k] * wv; a2 += condl[256 + k] * wv; a3 += condl[384 + k] * wv; }
;         float* o = modp + ((size_t)(ks * 2 + l) * 4) * MODW + col;
;         o[0] = a0; o[MODW] = a1; o[2 * MODW] = a2; o[3 * MODW] = a3;
	v_mov_b32_e32 v26, v40
	v_mov_b32_e32 v27, v36
	v_mov_b32_e32 v28, v33
	v_mov_b32_e32 v36, v41
	v_mov_b32_e32 v32, v34
	v_mov_b32_e32 v33, v30
	v_mov_b32_e32 v30, v35
	v_mov_b32_e32 v34, v42
	v_mov_b32_e32 v35, v38
	v_mov_b32_e32 v38, v43
	s_waitcnt vmcnt(20)
	v_pk_fma_f32 v[4:5], v[86:87], v[60:61], v[4:5] op_sel_hi:[0,1,1]
	v_pk_fma_f32 v[0:1], v[86:87], v[62:63], v[0:1] op_sel_hi:[0,1,1]
	v_pk_fma_f32 v[4:5], v[82:83], v[12:13], v[4:5] op_sel_hi:[0,1,1]
	v_pk_fma_f32 v[0:1], v[82:83], v[20:21], v[0:1] op_sel_hi:[0,1,1]
	v_pk_fma_f32 v[4:5], v[84:85], v[16:17], v[4:5] op_sel_hi:[0,1,1]
	v_pk_fma_f32 v[0:1], v[84:85], v[18:19], v[0:1] op_sel_hi:[0,1,1]
	s_waitcnt vmcnt(19)
	v_pk_fma_f32 v[4:5], v[88:89], v[14:15], v[4:5] op_sel_hi:[0,1,1]
	v_pk_fma_f32 v[0:1], v[88:89], v[22:23], v[0:1] op_sel_hi:[0,1,1]
	v_pk_fma_f32 v[4:5], v[80:81], v[24:25], v[4:5] op_sel_hi:[0,1,1]
	v_pk_fma_f32 v[0:1], v[80:81], v[26:27], v[0:1] op_sel_hi:[0,1,1]
	s_waitcnt vmcnt(18)
	v_pk_fma_f32 v[4:5], v[90:91], v[28:29], v[4:5] op_sel_hi:[0,1,1]
	v_pk_fma_f32 v[0:1], v[90:91], v[36:37], v[0:1] op_sel_hi:[0,1,1]
	s_waitcnt vmcnt(17)
	v_pk_fma_f32 v[4:5], v[92:93], v[32:33], v[4:5] op_sel_hi:[0,1,1]
	v_pk_fma_f32 v[0:1], v[92:93], v[34:35], v[0:1] op_sel_hi:[0,1,1]
	s_waitcnt vmcnt(16)
	v_pk_fma_f32 v[4:5], v[94:95], v[30:31], v[4:5] op_sel_hi:[0,1,1]
	v_pk_fma_f32 v[0:1], v[94:95], v[38:39], v[0:1] op_sel_hi:[0,1,1]
	v_add_co_u32_e64 v14, s[4:5], s14, v6
	v_add_co_u32_e32 v12, vcc, 0xfffd0000, v6
	s_nop 0
	v_addc_co_u32_e64 v15, s[4:5], -1, v7, s[4:5]
	v_add_co_u32_e64 v16, s[4:5], s15, v6
	global_load_dword v80, v[6:7], off
	s_nop 0
	v_addc_co_u32_e64 v17, s[4:5], -1, v7, s[4:5]
	v_add_co_u32_e64 v18, s[4:5], s16, v6
	v_addc_co_u32_e32 v13, vcc, -1, v7, vcc
	s_nop 0
	v_addc_co_u32_e64 v19, s[4:5], -1, v7, s[4:5]
	v_add_co_u32_e64 v20, s[4:5], s13, v6
	s_nop 1
	v_addc_co_u32_e64 v21, s[4:5], 0, v7, s[4:5]
	v_add_co_u32_e64 v22, s[4:5], s17, v6
	s_nop 1
	v_addc_co_u32_e64 v23, s[4:5], 0, v7, s[4:5]
	v_add_co_u32_e64 v24, s[4:5], s18, v6
	s_nop 1
	v_addc_co_u32_e64 v25, s[4:5], 0, v7, s[4:5]
	global_load_dword v82, v[14:15], off
	global_load_dword v84, v[16:17], off
	global_load_dword v86, v[12:13], off
	global_load_dword v88, v[18:19], off
	global_load_dword v90, v[20:21], off
	global_load_dword v92, v[22:23], off
	global_load_dword v94, v[24:25], off
	v_lshl_add_u64 v[6:7], v[6:7], 0, s[10:11]
	ds_read_b128 v[12:15], v11 offset:96
	ds_read_b128 v[16:19], v11 offset:608
	ds_read_b128 v[20:23], v11 offset:1120
	ds_read_b128 v[24:27], v11 offset:1632
	ds_read_b128 v[28:31], v11 offset:112
	ds_read_b128 v[32:35], v11 offset:624
	ds_read_b128 v[36:39], v11 offset:1136
	ds_read_b128 v[40:43], v11 offset:1648
	s_waitcnt lgkmcnt(6)
	v_mov_b32_e32 v60, v16
	v_mov_b32_e32 v61, v12
	s_waitcnt lgkmcnt(4)
	v_mov_b32_e32 v62, v24
	v_mov_b32_e32 v63, v20
	v_mov_b32_e32 v12, v17
	v_mov_b32_e32 v20, v25
	v_mov_b32_e32 v16, v18
	v_mov_b32_e32 v17, v14
	v_mov_b32_e32 v14, v19
	v_mov_b32_e32 v18, v26
	v_mov_b32_e32 v19, v22
	v_mov_b32_e32 v22, v27
	s_waitcnt lgkmcnt(2)
	v_mov_b32_e32 v24, v32
	v_mov_b32_e32 v25, v28
	s_waitcnt lgkmcnt(0)
	v_mov_b32_e32 v26, v40
	v_mov_b32_e32 v27, v36
	v_mov_b32_e32 v28, v33
	v_mov_b32_e32 v36, v41
	v_mov_b32_e32 v32, v34
	v_mov_b32_e32 v33, v30
	v_mov_b32_e32 v30, v35
	v_mov_b32_e32 v34, v42
	v_mov_b32_e32 v35, v38
	v_mov_b32_e32 v38, v43
	s_waitcnt vmcnt(20)
	v_pk_fma_f32 v[4:5], v[50:51], v[60:61], v[4:5] op_sel_hi:[0,1,1]
	v_pk_fma_f32 v[0:1], v[50:51], v[62:63], v[0:1] op_sel_hi:[0,1,1]
	v_pk_fma_f32 v[4:5], v[46:47], v[12:13], v[4:5] op_sel_hi:[0,1,1]
	v_pk_fma_f32 v[0:1], v[46:47], v[20:21], v[0:1] op_sel_hi:[0,1,1]
	v_pk_fma_f32 v[4:5], v[48:49], v[16:17], v[4:5] op_sel_hi:[0,1,1]
	v_pk_fma_f32 v[0:1], v[48:49], v[18:19], v[0:1] op_sel_hi:[0,1,1]
	s_waitcnt vmcnt(19)
	v_pk_fma_f32 v[4:5], v[52:53], v[14:15], v[4:5] op_sel_hi:[0,1,1]
	v_pk_fma_f32 v[0:1], v[52:53], v[22:23], v[0:1] op_sel_hi:[0,1,1]
	v_pk_fma_f32 v[4:5], v[44:45], v[24:25], v[4:5] op_sel_hi:[0,1,1]
	v_pk_fma_f32 v[0:1], v[44:45], v[26:27], v[0:1] op_sel_hi:[0,1,1]
	s_waitcnt vmcnt(18)
	v_pk_fma_f32 v[4:5], v[54:55], v[28:29], v[4:5] op_sel_hi:[0,1,1]
	v_pk_fma_f32 v[0:1], v[54:55], v[36:37], v[0:1] op_sel_hi:[0,1,1]
	s_waitcnt vmcnt(17)
	v_pk_fma_f32 v[4:5], v[56:57], v[32:33], v[4:5] op_sel_hi:[0,1,1]
	v_pk_fma_f32 v[0:1], v[56:57], v[34:35], v[0:1] op_sel_hi:[0,1,1]
	s_waitcnt vmcnt(16)
	v_pk_fma_f32 v[4:5], v[58:59], v[30:31], v[4:5] op_sel_hi:[0,1,1]
	v_pk_fma_f32 v[0:1], v[58:59], v[38:39], v[0:1] op_sel_hi:[0,1,1]
	v_add_co_u32_e64 v14, s[4:5], s14, v6
	v_add_co_u32_e32 v12, vcc, 0xfffd0000, v6
	s_nop 0
	v_addc_co_u32_e64 v15, s[4:5], -1, v7, s[4:5]
	v_add_co_u32_e64 v16, s[4:5], s15, v6
	global_load_dword v44, v[6:7], off
	s_nop 0
	v_addc_co_u32_e64 v17, s[4:5], -1, v7, s[4:5]
	v_add_co_u32_e64 v18, s[4:5], s16, v6
	v_addc_co_u32_e32 v13, vcc, -1, v7, vcc
	s_nop 0
	v_addc_co_u32_e64 v19, s[4:5], -1, v7, s[4:5]
	v_add_co_u32_e64 v20, s[4:5], s13, v6
	s_nop 1
	v_addc_co_u32_e64 v21, s[4:5], 0, v7, s[4:5]
	v_add_co_u32_e64 v22, s[4:5], s17, v6
	s_nop 1
	v_addc_co_u32_e64 v23, s[4:5], 0, v7, s[4:5]
	v_add_co_u32_e64 v24, s[4:5], s18, v6
	s_nop 1
	v_addc_co_u32_e64 v25, s[4:5], 0, v7, s[4:5]
	global_load_dword v46, v[14:15], off
	global_load_dword v48, v[16:17], off
	global_load_dword v50, v[12:13], off
	global_load_dword v52, v[18:19], off
	global_load_dword v54, v[20:21], off
	global_load_dword v56, v[22:23], off
	global_load_dword v58, v[24:25], off
	v_lshl_add_u64 v[6:7], v[6:7], 0, s[10:11]
	ds_read_b128 v[12:15], v11 offset:128
	ds_read_b128 v[16:19], v11 offset:640
	ds_read_b128 v[20:23], v11 offset:1152
	ds_read_b128 v[24:27], v11 offset:1664
	ds_read_b128 v[28:31], v11 offset:144
	ds_read_b128 v[32:35], v11 offset:656
	ds_read_b128 v[36:39], v11 offset:1168
	ds_read_b128 v[40:43], v11 offset:1680
	s_waitcnt lgkmcnt(6)
; DI void ada_partials(const P& p, LAS unsigned char* L) {
;     ...
; #pragma unroll 8
;         for (int k = 0; k < 128; ++k) { const float wv = w[(size_t)k * MODW]; a0 += condl[k] * wv; a1 += condl[128 + k] * wv; a2 += condl[256 + k] * wv; a3 += condl[384 + k] * wv; }
	v_mov_b32_e32 v60, v16
	v_mov_b32_e32 v61, v12
	s_waitcnt lgkmcnt(4)
	v_mov_b32_e32 v62, v24
	v_mov_b32_e32 v63, v20
	v_mov_b32_e32 v12, v17
	v_mov_b32_e32 v20, v25
	v_mov_b32_e32 v16, v18
	v_mov_b32_e32 v17, v14
	v_mov_b32_e32 v14, v19
	v_mov_b32_e32 v18, v26
	v_mov_b32_e32 v19, v22
	v_mov_b32_e32 v22, v27
	s_waitcnt lgkmcnt(2)
	v_mov_b32_e32 v24, v32
	v_mov_b32_e32 v25, v28
	s_waitcnt lgkmcnt(0)
	v_mov_b32_e32 v26, v40
	v_mov_b32_e32 v27, v36
	v_mov_b32_e32 v28, v33
	v_mov_b32_e32 v36, v41
	v_mov_b32_e32 v32, v34
	v_mov_b32_e32 v33, v30
	v_mov_b32_e32 v30, v35
	v_mov_b32_e32 v34, v42
	v_mov_b32_e32 v35, v38
	v_mov_b32_e32 v38, v43
	s_waitcnt vmcnt(20)
	v_pk_fma_f32 v[4:5], v[70:71], v[60:61], v[4:5] op_sel_hi:[0,1,1]
	v_pk_fma_f32 v[0:1], v[70:71], v[62:63], v[0:1] op_sel_hi:[0,1,1]
	v_pk_fma_f32 v[4:5], v[66:67], v[12:13], v[4:5] op_sel_hi:[0,1,1]
	v_pk_fma_f32 v[0:1], v[66:67], v[20:21], v[0:1] op_sel_hi:[0,1,1]
	v_pk_fma_f32 v[4:5], v[68:69], v[16:17], v[4:5] op_sel_hi:[0,1,1]
	v_pk_fma_f32 v[0:1], v[68:69], v[18:19], v[0:1] op_sel_hi:[0,1,1]
	s_waitcnt vmcnt(19)
	v_pk_fma_f32 v[4:5], v[72:73], v[14:15], v[4:5] op_sel_hi:[0,1,1]
	v_pk_fma_f32 v[0:1], v[72:73], v[22:23], v[0:1] op_sel_hi:[0,1,1]
	v_pk_fma_f32 v[4:5], v[64:65], v[24:25], v[4:5] op_sel_hi:[0,1,1]
	v_pk_fma_f32 v[0:1], v[64:65], v[26:27], v[0:1] op_sel_hi:[0,1,1]
	s_waitcnt vmcnt(18)
	v_pk_fma_f32 v[4:5], v[74:75], v[28:29], v[4:5] op_sel_hi:[0,1,1]
	v_pk_fma_f32 v[0:1], v[74:75], v[36:37], v[0:1] op_sel_hi:[0,1,1]
	s_waitcnt vmcnt(17)
	v_pk_fma_f32 v[4:5], v[76:77], v[32:33], v[4:5] op_sel_hi:[0,1,1]
	v_pk_fma_f32 v[0:1], v[76:77], v[34:35], v[0:1] op_sel_hi:[0,1,1]
	s_waitcnt vmcnt(16)
	v_pk_fma_f32 v[4:5], v[78:79], v[30:31], v[4:5] op_sel_hi:[0,1,1]
	v_pk_fma_f32 v[0:1], v[78:79], v[38:39], v[0:1] op_sel_hi:[0,1,1]
	v_add_co_u32_e64 v14, s[4:5], s14, v6
	v_add_co_u32_e32 v12, vcc, 0xfffd0000, v6
	s_nop 0
	v_addc_co_u32_e64 v15, s[4:5], -1, v7, s[4:5]
	v_add_co_u32_e64 v16, s[4:5], s15, v6
	global_load_dword v64, v[6:7], off
	s_nop 0
	v_addc_co_u32_e64 v17, s[4:5], -1, v7, s[4:5]
	v_add_co_u32_e64 v18, s[4:5], s16, v6
	v_addc_co_u32_e32 v13, vcc, -1, v7, vcc
	s_nop 0
	v_addc_co_u32_e64 v19, s[4:5], -1, v7, s[4:5]
	v_add_co_u32_e64 v20, s[4:5], s13, v6
	s_nop 1
	v_addc_co_u32_e64 v21, s[4:5], 0, v7, s[4:5]
	v_add_co_u32_e64 v22, s[4:5], s17, v6
	s_nop 1
	v_addc_co_u32_e64 v23, s[4:5], 0, v7, s[4:5]
	v_add_co_u32_e64 v24, s[4:5], s18, v6
	s_nop 1
	v_addc_co_u32_e64 v25, s[4:5], 0, v7, s[4:5]
	global_load_dword v66, v[14:15], off
	global_load_dword v68, v[16:17], off
	global_load_dword v70, v[12:13], off
	global_load_dword v72, v[18:19], off
	global_load_dword v74, v[20:21], off
	global_load_dword v76, v[22:23], off
	global_load_dword v78, v[24:25], off
	v_lshl_add_u64 v[6:7], v[6:7], 0, s[10:11]
	ds_read_b128 v[12:15], v11 offset:160
	ds_read_b128 v[16:19], v11 offset:672
	ds_read_b128 v[20:23], v11 offset:1184
	ds_read_b128 v[24:27], v11 offset:1696
	ds_read_b128 v[28:31], v11 offset:176
	ds_read_b128 v[32:35], v11 offset:688
	ds_read_b128 v[36:39], v11 offset:1200
	ds_read_b128 v[40:43], v11 offset:1712
	s_waitcnt lgkmcnt(6)
	v_mov_b32_e32 v60, v16
	v_mov_b32_e32 v61, v12
	s_waitcnt lgkmcnt(4)
	v_mov_b32_e32 v62, v24
	v_mov_b32_e32 v63, v20
	v_mov_b32_e32 v12, v17
	v_mov_b32_e32 v20, v25
	v_mov_b32_e32 v16, v18
	v_mov_b32_e32 v17, v14
	v_mov_b32_e32 v14, v19
	v_mov_b32_e32 v18, v26
	v_mov_b32_e32 v19, v22
	v_mov_b32_e32 v22, v27
	s_waitcnt lgkmcnt(2)
	v_mov_b32_e32 v24, v32
	v_mov_b32_e32 v25, v28
	s_waitcnt lgkmcnt(0)
	v_mov_b32_e32 v26, v40
	v_mov_b32_e32 v27, v36
	v_mov_b32_e32 v28, v33
	v_mov_b32_e32 v36, v41
	v_mov_b32_e32 v32, v34
	v_mov_b32_e32 v33, v30
	v_mov_b32_e32 v30, v35
	v_mov_b32_e32 v34, v42
	v_mov_b32_e32 v35, v38
	v_mov_b32_e32 v38, v43
	s_waitcnt vmcnt(20)
	v_pk_fma_f32 v[4:5], v[86:87], v[60:61], v[4:5] op_sel_hi:[0,1,1]
	v_pk_fma_f32 v[0:1], v[86:87], v[62:63], v[0:1] op_sel_hi:[0,1,1]
	v_pk_fma_f32 v[4:5], v[82:83], v[12:13], v[4:5] op_sel_hi:[0,1,1]
	v_pk_fma_f32 v[0:1], v[82:83], v[20:21], v[0:1] op_sel_hi:[0,1,1]
	v_pk_fma_f32 v[4:5], v[84:85], v[16:17], v[4:5] op_sel_hi:[0,1,1]
	v_pk_fma_f32 v[0:1], v[84:85], v[18:19], v[0:1] op_sel_hi:[0,1,1]
	s_waitcnt vmcnt(19)
	v_pk_fma_f32 v[4:5], v[88:89], v[14:15], v[4:5] op_sel_hi:[0,1,1]
	v_pk_fma_f32 v[0:1], v[88:89], v[22:23], v[0:1] op_sel_hi:[0,1,1]
	v_pk_fma_f32 v[4:5], v[80:81], v[24:25], v[4:5] op_sel_hi:[0,1,1]
	v_pk_fma_f32 v[0:1], v[80:81], v[26:27], v[0:1] op_sel_hi:[0,1,1]
	s_waitcnt vmcnt(18)
	v_pk_fma_f32 v[4:5], v[90:91], v[28:29], v[4:5] op_sel_hi:[0,1,1]
	v_pk_fma_f32 v[0:1], v[90:91], v[36:37], v[0:1] op_sel_hi:[0,1,1]
	s_waitcnt vmcnt(17)
	v_pk_fma_f32 v[4:5], v[92:93], v[32:33], v[4:5] op_sel_hi:[0,1,1]
	v_pk_fma_f32 v[0:1], v[92:93], v[34:35], v[0:1] op_sel_hi:[0,1,1]
	s_waitcnt vmcnt(16)
	v_pk_fma_f32 v[4:5], v[94:95], v[30:31], v[4:5] op_sel_hi:[0,1,1]
	v_pk_fma_f32 v[0:1], v[94:95], v[38:39], v[0:1] op_sel_hi:[0,1,1]
	v_add_co_u32_e64 v14, s[4:5], s14, v6
	v_add_co_u32_e32 v12, vcc, 0xfffd0000, v6
	s_nop 0
	v_addc_co_u32_e64 v15, s[4:5], -1, v7, s[4:5]
	v_add_co_u32_e64 v16, s[4:5], s15, v6
	global_load_dword v80, v[6:7], off
	s_nop 0
	v_addc_co_u32_e64 v17, s[4:5], -1, v7, s[4:5]
	v_add_co_u32_e64 v18, s[4:5], s16, v6
	v_addc_co_u32_e32 v13, vcc, -1, v7, vcc
	s_nop 0
	v_addc_co_u32_e64 v19, s[4:5], -1, v7, s[4:5]
	v_add_co_u32_e64 v20, s[4:5], s13, v6
	s_nop 1
	v_addc_co_u32_e64 v21, s[4:5], 0, v7, s[4:5]
	v_add_co_u32_e64 v22, s[4:5], s17, v6
	s_nop 1
	v_addc_co_u32_e64 v23, s[4:5], 0, v7, s[4:5]
	v_add_co_u32_e64 v24, s[4:5], s18, v6
	s_nop 1
	v_addc_co_u32_e64 v25, s[4:5], 0, v7, s[4:5]
	global_load_dword v82, v[14:15], off
	global_load_dword v84, v[16:17], off
	global_load_dword v86, v[12:13], off
	global_load_dword v88, v[18:19], off
	global_load_dword v90, v[20:21], off
	global_load_dword v92, v[22:23], off
	global_load_dword v94, v[24:25], off
	v_lshl_add_u64 v[6:7], v[6:7], 0, s[10:11]
	ds_read_b128 v[12:15], v11 offset:192
	ds_read_b128 v[16:19], v11 offset:704
	ds_read_b128 v[20:23], v11 offset:1216
	ds_read_b128 v[24:27], v11 offset:1728
	ds_read_b128 v[28:31], v11 offset:208
	ds_read_b128 v[32:35], v11 offset:720
	ds_read_b128 v[36:39], v11 offset:1232
	ds_read_b128 v[40:43], v11 offset:1744
	s_waitcnt lgkmcnt(6)
; DI void ada_partials(const P& p, LAS unsigned char* L) {
;     ...
; #pragma unroll 8
;         for (int k = 0; k < 128; ++k) { const float wv = w[(size_t)k * MODW]; a0 += condl[k] * wv; a1 += condl[128 + k] * wv; a2 += condl[256 + k] * wv; a3 += condl[384 + k] * wv; }
	v_mov_b32_e32 v60, v16
	v_mov_b32_e32 v61, v12
	s_waitcnt lgkmcnt(4)
	v_mov_b32_e32 v62, v24
	v_mov_b32_e32 v63, v20
	v_mov_b32_e32 v12, v17
	v_mov_b32_e32 v20, v25
	v_mov_b32_e32 v16, v18
	v_mov_b32_e32 v17, v14
	v_mov_b32_e32 v14, v19
	v_mov_b32_e32 v18, v26
	v_mov_b32_e32 v19, v22
	v_mov_b32_e32 v22, v27
	s_waitcnt lgkmcnt(2)
	v_mov_b32_e32 v24, v32
	v_mov_b32_e32 v25, v28
	s_waitcnt lgkmcnt(0)
	v_mov_b32_e32 v26, v40
	v_mov_b32_e32 v27, v36
	v_mov_b32_e32 v28, v33
	v_mov_b32_e32 v36, v41
	v_mov_b32_e32 v32, v34
	v_mov_b32_e32 v33, v30
	v_mov_b32_e32 v30, v35
	v_mov_b32_e32 v34, v42
	v_mov_b32_e32 v35, v38
	v_mov_b32_e32 v38, v43
	s_waitcnt vmcnt(20)
	v_pk_fma_f32 v[4:5], v[50:51], v[60:61], v[4:5] op_sel_hi:[0,1,1]
	v_pk_fma_f32 v[0:1], v[50:51], v[62:63], v[0:1] op_sel_hi:[0,1,1]
	v_pk_fma_f32 v[4:5], v[46:47], v[12:13], v[4:5] op_sel_hi:[0,1,1]
	v_pk_fma_f32 v[0:1], v[46:47], v[20:21], v[0:1] op_sel_hi:[0,1,1]
	v_pk_fma_f32 v[4:5], v[48:49], v[16:17], v[4:5] op_sel_hi:[0,1,1]
	v_pk_fma_f32 v[0:1], v[48:49], v[18:19], v[0:1] op_sel_hi:[0,1,1]
	s_waitcnt vmcnt(19)
	v_pk_fma_f32 v[4:5], v[52:53], v[14:15], v[4:5] op_sel_hi:[0,1,1]
	v_pk_fma_f32 v[0:1], v[52:53], v[22:23], v[0:1] op_sel_hi:[0,1,1]
	v_pk_fma_f32 v[4:5], v[44:45], v[24:25], v[4:5] op_sel_hi:[0,1,1]
	v_pk_fma_f32 v[0:1], v[44:45], v[26:27], v[0:1] op_sel_hi:[0,1,1]
	s_waitcnt vmcnt(18)
	v_pk_fma_f32 v[4:5], v[54:55], v[28:29], v[4:5] op_sel_hi:[0,1,1]
	v_pk_fma_f32 v[0:1], v[54:55], v[36:37], v[0:1] op_sel_hi:[0,1,1]
	s_waitcnt vmcnt(17)
	v_pk_fma_f32 v[4:5], v[56:57], v[32:33], v[4:5] op_sel_hi:[0,1,1]
	v_pk_fma_f32 v[0:1], v[56:57], v[34:35], v[0:1] op_sel_hi:[0,1,1]
	s_waitcnt vmcnt(16)
	v_pk_fma_f32 v[4:5], v[58:59], v[30:31], v[4:5] op_sel_hi:[0,1,1]
	v_pk_fma_f32 v[0:1], v[58:59], v[38:39], v[0:1] op_sel_hi:[0,1,1]
	v_add_co_u32_e64 v14, s[4:5], s14, v6
	v_add_co_u32_e32 v12, vcc, 0xfffd0000, v6
	s_nop 0
	v_addc_co_u32_e64 v15, s[4:5], -1, v7, s[4:5]
	v_add_co_u32_e64 v16, s[4:5], s15, v6
	global_load_dword v44, v[6:7], off
	s_nop 0
	v_addc_co_u32_e64 v17, s[4:5], -1, v7, s[4:5]
	v_add_co_u32_e64 v18, s[4:5], s16, v6
	v_addc_co_u32_e32 v13, vcc, -1, v7, vcc
	s_nop 0
	v_addc_co_u32_e64 v19, s[4:5], -1, v7, s[4:5]
	v_add_co_u32_e64 v20, s[4:5], s13, v6
	s_nop 1
	v_addc_co_u32_e64 v21, s[4:5], 0, v7, s[4:5]
	v_add_co_u32_e64 v22, s[4:5], s17, v6
	s_nop 1
	v_addc_co_u32_e64 v23, s[4:5], 0, v7, s[4:5]
	v_add_co_u32_e64 v24, s[4:5], s18, v6
	s_nop 1
	v_addc_co_u32_e64 v25, s[4:5], 0, v7, s[4:5]
	global_load_dword v46, v[14:15], off
	global_load_dword v48, v[16:17], off
	global_load_dword v50, v[12:13], off
	global_load_dword v52, v[18:19], off
	global_load_dword v54, v[20:21], off
	global_load_dword v56, v[22:23], off
	global_load_dword v58, v[24:25], off
	v_lshl_add_u64 v[6:7], v[6:7], 0, s[10:11]
	ds_read_b128 v[12:15], v11 offset:224
	ds_read_b128 v[16:19], v11 offset:736
	ds_read_b128 v[20:23], v11 offset:1248
	ds_read_b128 v[24:27], v11 offset:1760
	ds_read_b128 v[28:31], v11 offset:240
	ds_read_b128 v[32:35], v11 offset:752
	ds_read_b128 v[36:39], v11 offset:1264
	ds_read_b128 v[40:43], v11 offset:1776
	s_waitcnt lgkmcnt(6)
	v_mov_b32_e32 v60, v16
	v_mov_b32_e32 v61, v12
	s_waitcnt lgkmcnt(4)
	v_mov_b32_e32 v62, v24
	v_mov_b32_e32 v63, v20
	v_mov_b32_e32 v12, v17
	v_mov_b32_e32 v20, v25
	v_mov_b32_e32 v16, v18
	v_mov_b32_e32 v17, v14
	v_mov_b32_e32 v14, v19
	v_mov_b32_e32 v18, v26
	v_mov_b32_e32 v19, v22
	v_mov_b32_e32 v22, v27
	s_waitcnt lgkmcnt(2)
	v_mov_b32_e32 v24, v32
	v_mov_b32_e32 v25, v28
	s_waitcnt lgkmcnt(0)
	v_mov_b32_e32 v26, v40
	v_mov_b32_e32 v27, v36
	v_mov_b32_e32 v28, v33
	v_mov_b32_e32 v36, v41
	v_mov_b32_e32 v32, v34
	v_mov_b32_e32 v33, v30
	v_mov_b32_e32 v30, v35
	v_mov_b32_e32 v34, v42
	v_mov_b32_e32 v35, v38
	v_mov_b32_e32 v38, v43
	s_waitcnt vmcnt(20)
	v_pk_fma_f32 v[4:5], v[70:71], v[60:61], v[4:5] op_sel_hi:[0,1,1]
	v_pk_fma_f32 v[0:1], v[70:71], v[62:63], v[0:1] op_sel_hi:[0,1,1]
	v_pk_fma_f32 v[4:5], v[66:67], v[12:13], v[4:5] op_sel_hi:[0,1,1]
	v_pk_fma_f32 v[0:1], v[66:67], v[20:21], v[0:1] op_sel_hi:[0,1,1]
	v_pk_fma_f32 v[4:5], v[68:69], v[16:17], v[4:5] op_sel_hi:[0,1,1]
	v_pk_fma_f32 v[0:1], v[68:69], v[18:19], v[0:1] op_sel_hi:[0,1,1]
	s_waitcnt vmcnt(19)
	v_pk_fma_f32 v[4:5], v[72:73], v[14:15], v[4:5] op_sel_hi:[0,1,1]
	v_pk_fma_f32 v[0:1], v[72:73], v[22:23], v[0:1] op_sel_hi:[0,1,1]
	v_pk_fma_f32 v[4:5], v[64:65], v[24:25], v[4:5] op_sel_hi:[0,1,1]
	v_pk_fma_f32 v[0:1], v[64:65], v[26:27], v[0:1] op_sel_hi:[0,1,1]
	s_waitcnt vmcnt(18)
	v_pk_fma_f32 v[4:5], v[74:75], v[28:29], v[4:5] op_sel_hi:[0,1,1]
	v_pk_fma_f32 v[0:1], v[74:75], v[36:37], v[0:1] op_sel_hi:[0,1,1]
	s_waitcnt vmcnt(17)
	v_pk_fma_f32 v[4:5], v[76:77], v[32:33], v[4:5] op_sel_hi:[0,1,1]
	v_pk_fma_f32 v[0:1], v[76:77], v[34:35], v[0:1] op_sel_hi:[0,1,1]
	s_waitcnt vmcnt(16)
	v_pk_fma_f32 v[4:5], v[78:79], v[30:31], v[4:5] op_sel_hi:[0,1,1]
	v_pk_fma_f32 v[0:1], v[78:79], v[38:39], v[0:1] op_sel_hi:[0,1,1]
	v_add_co_u32_e64 v14, s[4:5], s14, v6
	v_add_co_u32_e32 v12, vcc, 0xfffd0000, v6
	s_nop 0
	v_addc_co_u32_e64 v15, s[4:5], -1, v7, s[4:5]
	v_add_co_u32_e64 v16, s[4:5], s15, v6
	global_load_dword v64, v[6:7], off
	s_nop 0
	v_addc_co_u32_e64 v17, s[4:5], -1, v7, s[4:5]
	v_add_co_u32_e64 v18, s[4:5], s16, v6
	v_addc_co_u32_e32 v13, vcc, -1, v7, vcc
	s_nop 0
	v_addc_co_u32_e64 v19, s[4:5], -1, v7, s[4:5]
	v_add_co_u32_e64 v20, s[4:5], s13, v6
	s_nop 1
	v_addc_co_u32_e64 v21, s[4:5], 0, v7, s[4:5]
	v_add_co_u32_e64 v22, s[4:5], s17, v6
	s_nop 1
	v_addc_co_u32_e64 v23, s[4:5], 0, v7, s[4:5]
	v_add_co_u32_e64 v24, s[4:5], s18, v6
	s_nop 1
	v_addc_co_u32_e64 v25, s[4:5], 0, v7, s[4:5]
	global_load_dword v66, v[14:15], off
	global_load_dword v68, v[16:17], off
	global_load_dword v70, v[12:13], off
	global_load_dword v72, v[18:19], off
	global_load_dword v74, v[20:21], off
	global_load_dword v76, v[22:23], off
	global_load_dword v78, v[24:25], off
	v_lshl_add_u64 v[6:7], v[6:7], 0, s[10:11]
	ds_read_b128 v[12:15], v11 offset:256
	ds_read_b128 v[16:19], v11 offset:768
	ds_read_b128 v[20:23], v11 offset:1280
	ds_read_b128 v[24:27], v11 offset:1792
	ds_read_b128 v[28:31], v11 offset:272
	ds_read_b128 v[32:35], v11 offset:784
	ds_read_b128 v[36:39], v11 offset:1296
	ds_read_b128 v[40:43], v11 offset:1808
	s_waitcnt lgkmcnt(6)
; DI void ada_partials(const P& p, LAS unsigned char* L) {
;     ...
; #pragma unroll 8
;         for (int k = 0; k < 128; ++k) { const float wv = w[(size_t)k * MODW]; a0 += condl[k] * wv; a1 += condl[128 + k] * wv; a2 += condl[256 + k] * wv; a3 += condl[384 + k] * wv; }
	v_mov_b32_e32 v60, v16
	v_mov_b32_e32 v61, v12
	s_waitcnt lgkmcnt(4)
	v_mov_b32_e32 v62, v24
	v_mov_b32_e32 v63, v20
	v_mov_b32_e32 v12, v17
	v_mov_b32_e32 v20, v25
	v_mov_b32_e32 v16, v18
	v_mov_b32_e32 v17, v14
	v_mov_b32_e32 v14, v19
	v_mov_b32_e32 v18, v26
	v_mov_b32_e32 v19, v22
	v_mov_b32_e32 v22, v27
	s_waitcnt lgkmcnt(2)
	v_mov_b32_e32 v24, v32
	v_mov_b32_e32 v25, v28
	s_waitcnt lgkmcnt(0)
	v_mov_b32_e32 v26, v40
	v_mov_b32_e32 v27, v36
	v_mov_b32_e32 v28, v33
	v_mov_b32_e32 v36, v41
	v_mov_b32_e32 v32, v34
	v_mov_b32_e32 v33, v30
	v_mov_b32_e32 v30, v35
	v_mov_b32_e32 v34, v42
	v_mov_b32_e32 v35, v38
	v_mov_b32_e32 v38, v43
	s_waitcnt vmcnt(20)
	v_pk_fma_f32 v[4:5], v[86:87], v[60:61], v[4:5] op_sel_hi:[0,1,1]
	v_pk_fma_f32 v[0:1], v[86:87], v[62:63], v[0:1] op_sel_hi:[0,1,1]
	v_pk_fma_f32 v[4:5], v[82:83], v[12:13], v[4:5] op_sel_hi:[0,1,1]
	v_pk_fma_f32 v[0:1], v[82:83], v[20:21], v[0:1] op_sel_hi:[0,1,1]
	v_pk_fma_f32 v[4:5], v[84:85], v[16:17], v[4:5] op_sel_hi:[0,1,1]
	v_pk_fma_f32 v[0:1], v[84:85], v[18:19], v[0:1] op_sel_hi:[0,1,1]
	s_waitcnt vmcnt(19)
	v_pk_fma_f32 v[4:5], v[88:89], v[14:15], v[4:5] op_sel_hi:[0,1,1]
	v_pk_fma_f32 v[0:1], v[88:89], v[22:23], v[0:1] op_sel_hi:[0,1,1]
	v_pk_fma_f32 v[4:5], v[80:81], v[24:25], v[4:5] op_sel_hi:[0,1,1]
	v_pk_fma_f32 v[0:1], v[80:81], v[26:27], v[0:1] op_sel_hi:[0,1,1]
	s_waitcnt vmcnt(18)
	v_pk_fma_f32 v[4:5], v[90:91], v[28:29], v[4:5] op_sel_hi:[0,1,1]
	v_pk_fma_f32 v[0:1], v[90:91], v[36:37], v[0:1] op_sel_hi:[0,1,1]
	s_waitcnt vmcnt(17)
	v_pk_fma_f32 v[4:5], v[92:93], v[32:33], v[4:5] op_sel_hi:[0,1,1]
	v_pk_fma_f32 v[0:1], v[92:93], v[34:35], v[0:1] op_sel_hi:[0,1,1]
	s_waitcnt vmcnt(16)
	v_pk_fma_f32 v[4:5], v[94:95], v[30:31], v[4:5] op_sel_hi:[0,1,1]
	v_pk_fma_f32 v[0:1], v[94:95], v[38:39], v[0:1] op_sel_hi:[0,1,1]
	v_add_co_u32_e64 v14, s[4:5], s14, v6
	v_add_co_u32_e32 v12, vcc, 0xfffd0000, v6
	s_nop 0
	v_addc_co_u32_e64 v15, s[4:5], -1, v7, s[4:5]
	v_add_co_u32_e64 v16, s[4:5], s15, v6
	global_load_dword v80, v[6:7], off
	s_nop 0
	v_addc_co_u32_e64 v17, s[4:5], -1, v7, s[4:5]
	v_add_co_u32_e64 v18, s[4:5], s16, v6
	v_addc_co_u32_e32 v13, vcc, -1, v7, vcc
	s_nop 0
	v_addc_co_u32_e64 v19, s[4:5], -1, v7, s[4:5]
	v_add_co_u32_e64 v20, s[4:5], s13, v6
	s_nop 1
	v_addc_co_u32_e64 v21, s[4:5], 0, v7, s[4:5]
	v_add_co_u32_e64 v22, s[4:5], s17, v6
	s_nop 1
	v_addc_co_u32_e64 v23, s[4:5], 0, v7, s[4:5]
	v_add_co_u32_e64 v24, s[4:5], s18, v6
	s_nop 1
	v_addc_co_u32_e64 v25, s[4:5], 0, v7, s[4:5]
	global_load_dword v82, v[14:15], off
	global_load_dword v84, v[16:17], off
	global_load_dword v86, v[12:13], off
	global_load_dword v88, v[18:19], off
	global_load_dword v90, v[20:21], off
	global_load_dword v92, v[22:23], off
	global_load_dword v94, v[24:25], off
	v_lshl_add_u64 v[6:7], v[6:7], 0, s[10:11]
	ds_read_b128 v[12:15], v11 offset:288
	ds_read_b128 v[16:19], v11 offset:800
	ds_read_b128 v[20:23], v11 offset:1312
	ds_read_b128 v[24:27], v11 offset:1824
	ds_read_b128 v[28:31], v11 offset:304
	ds_read_b128 v[32:35], v11 offset:816
	ds_read_b128 v[36:39], v11 offset:1328
	ds_read_b128 v[40:43], v11 offset:1840
	s_waitcnt lgkmcnt(6)
	v_mov_b32_e32 v60, v16
	v_mov_b32_e32 v61, v12
	s_waitcnt lgkmcnt(4)
	v_mov_b32_e32 v62, v24
	v_mov_b32_e32 v63, v20
	v_mov_b32_e32 v12, v17
	v_mov_b32_e32 v20, v25
	v_mov_b32_e32 v16, v18
	v_mov_b32_e32 v17, v14
	v_mov_b32_e32 v14, v19
	v_mov_b32_e32 v18, v26
	v_mov_b32_e32 v19, v22
	v_mov_b32_e32 v22, v27
	s_waitcnt lgkmcnt(2)
	v_mov_b32_e32 v24, v32
	v_mov_b32_e32 v25, v28
	s_waitcnt lgkmcnt(0)
	v_mov_b32_e32 v26, v40
	v_mov_b32_e32 v27, v36
	v_mov_b32_e32 v28, v33
	v_mov_b32_e32 v36, v41
	v_mov_b32_e32 v32, v34
	v_mov_b32_e32 v33, v30
	v_mov_b32_e32 v30, v35
	v_mov_b32_e32 v34, v42
	v_mov_b32_e32 v35, v38
	v_mov_b32_e32 v38, v43
	s_waitcnt vmcnt(20)
	v_pk_fma_f32 v[4:5], v[50:51], v[60:61], v[4:5] op_sel_hi:[0,1,1]
	v_pk_fma_f32 v[0:1], v[50:51], v[62:63], v[0:1] op_sel_hi:[0,1,1]
	v_pk_fma_f32 v[4:5], v[46:47], v[12:13], v[4:5] op_sel_hi:[0,1,1]
	v_pk_fma_f32 v[0:1], v[46:47], v[20:21], v[0:1] op_sel_hi:[0,1,1]
	v_pk_fma_f32 v[4:5], v[48:49], v[16:17], v[4:5] op_sel_hi:[0,1,1]
	v_pk_fma_f32 v[0:1], v[48:49], v[18:19], v[0:1] op_sel_hi:[0,1,1]
	s_waitcnt vmcnt(19)
	v_pk_fma_f32 v[4:5], v[52:53], v[14:15], v[4:5] op_sel_hi:[0,1,1]
	v_pk_fma_f32 v[0:1], v[52:53], v[22:23], v[0:1] op_sel_hi:[0,1,1]
	v_pk_fma_f32 v[4:5], v[44:45], v[24:25], v[4:5] op_sel_hi:[0,1,1]
	v_pk_fma_f32 v[0:1], v[44:45], v[26:27], v[0:1] op_sel_hi:[0,1,1]
	s_waitcnt vmcnt(18)
	v_pk_fma_f32 v[4:5], v[54:55], v[28:29], v[4:5] op_sel_hi:[0,1,1]
	v_pk_fma_f32 v[0:1], v[54:55], v[36:37], v[0:1] op_sel_hi:[0,1,1]
	s_waitcnt vmcnt(17)
	v_pk_fma_f32 v[4:5], v[56:57], v[32:33], v[4:5] op_sel_hi:[0,1,1]
	v_pk_fma_f32 v[0:1], v[56:57], v[34:35], v[0:1] op_sel_hi:[0,1,1]
	s_waitcnt vmcnt(16)
	v_pk_fma_f32 v[4:5], v[58:59], v[30:31], v[4:5] op_sel_hi:[0,1,1]
	v_pk_fma_f32 v[0:1], v[58:59], v[38:39], v[0:1] op_sel_hi:[0,1,1]
	v_add_co_u32_e64 v14, s[4:5], s14, v6
	v_add_co_u32_e32 v12, vcc, 0xfffd0000, v6
	s_nop 0
	v_addc_co_u32_e64 v15, s[4:5], -1, v7, s[4:5]
	v_add_co_u32_e64 v16, s[4:5], s15, v6
	global_load_dword v44, v[6:7], off
	s_nop 0
	v_addc_co_u32_e64 v17, s[4:5], -1, v7, s[4:5]
	v_add_co_u32_e64 v18, s[4:5], s16, v6
	v_addc_co_u32_e32 v13, vcc, -1, v7, vcc
	s_nop 0
	v_addc_co_u32_e64 v19, s[4:5], -1, v7, s[4:5]
	v_add_co_u32_e64 v20, s[4:5], s13, v6
	s_nop 1
	v_addc_co_u32_e64 v21, s[4:5], 0, v7, s[4:5]
	v_add_co_u32_e64 v22, s[4:5], s17, v6
	s_nop 1
	v_addc_co_u32_e64 v23, s[4:5], 0, v7, s[4:5]
	v_add_co_u32_e64 v24, s[4:5], s18, v6
	s_nop 1
	v_addc_co_u32_e64 v25, s[4:5], 0, v7, s[4:5]
	global_load_dword v46, v[14:15], off
	global_load_dword v48, v[16:17], off
	global_load_dword v50, v[12:13], off
	global_load_dword v52, v[18:19], off
	global_load_dword v54, v[20:21], off
	global_load_dword v56, v[22:23], off
	global_load_dword v58, v[24:25], off
	v_lshl_add_u64 v[6:7], v[6:7], 0, s[10:11]
	ds_read_b128 v[12:15], v11 offset:320
	ds_read_b128 v[16:19], v11 offset:832
	ds_read_b128 v[20:23], v11 offset:1344
	ds_read_b128 v[24:27], v11 offset:1856
	ds_read_b128 v[28:31], v11 offset:336
	ds_read_b128 v[32:35], v11 offset:848
	ds_read_b128 v[36:39], v11 offset:1360
	ds_read_b128 v[40:43], v11 offset:1872
	s_waitcnt lgkmcnt(6)
; DI void ada_partials(const P& p, LAS unsigned char* L) {
;     ...
; #pragma unroll 8
;         for (int k = 0; k < 128; ++k) { const float wv = w[(size_t)k * MODW]; a0 += condl[k] * wv; a1 += condl[128 + k] * wv; a2 += condl[256 + k] * wv; a3 += condl[384 + k] * wv; }
	v_mov_b32_e32 v60, v16
	v_mov_b32_e32 v61, v12
	s_waitcnt lgkmcnt(4)
	v_mov_b32_e32 v62, v24
	v_mov_b32_e32 v63, v20
	v_mov_b32_e32 v12, v17
	v_mov_b32_e32 v20, v25
	v_mov_b32_e32 v16, v18
	v_mov_b32_e32 v17, v14
	v_mov_b32_e32 v14, v19
	v_mov_b32_e32 v18, v26
	v_mov_b32_e32 v19, v22
	v_mov_b32_e32 v22, v27
	s_waitcnt lgkmcnt(2)
	v_mov_b32_e32 v24, v32
	v_mov_b32_e32 v25, v28
	s_waitcnt lgkmcnt(0)
	v_mov_b32_e32 v26, v40
	v_mov_b32_e32 v27, v36
	v_mov_b32_e32 v28, v33
	v_mov_b32_e32 v36, v41
	v_mov_b32_e32 v32, v34
	v_mov_b32_e32 v33, v30
	v_mov_b32_e32 v30, v35
	v_mov_b32_e32 v34, v42
	v_mov_b32_e32 v35, v38
	v_mov_b32_e32 v38, v43
	s_waitcnt vmcnt(20)
	v_pk_fma_f32 v[4:5], v[70:71], v[60:61], v[4:5] op_sel_hi:[0,1,1]
	v_pk_fma_f32 v[0:1], v[70:71], v[62:63], v[0:1] op_sel_hi:[0,1,1]
	v_pk_fma_f32 v[4:5], v[66:67], v[12:13], v[4:5] op_sel_hi:[0,1,1]
	v_pk_fma_f32 v[0:1], v[66:67], v[20:21], v[0:1] op_sel_hi:[0,1,1]
	v_pk_fma_f32 v[4:5], v[68:69], v[16:17], v[4:5] op_sel_hi:[0,1,1]
	v_pk_fma_f32 v[0:1], v[68:69], v[18:19], v[0:1] op_sel_hi:[0,1,1]
	s_waitcnt vmcnt(19)
	v_pk_fma_f32 v[4:5], v[72:73], v[14:15], v[4:5] op_sel_hi:[0,1,1]
	v_pk_fma_f32 v[0:1], v[72:73], v[22:23], v[0:1] op_sel_hi:[0,1,1]
	v_pk_fma_f32 v[4:5], v[64:65], v[24:25], v[4:5] op_sel_hi:[0,1,1]
	v_pk_fma_f32 v[0:1], v[64:65], v[26:27], v[0:1] op_sel_hi:[0,1,1]
	s_waitcnt vmcnt(18)
	v_pk_fma_f32 v[4:5], v[74:75], v[28:29], v[4:5] op_sel_hi:[0,1,1]
	v_pk_fma_f32 v[0:1], v[74:75], v[36:37], v[0:1] op_sel_hi:[0,1,1]
	s_waitcnt vmcnt(17)
	v_pk_fma_f32 v[4:5], v[76:77], v[32:33], v[4:5] op_sel_hi:[0,1,1]
	v_pk_fma_f32 v[0:1], v[76:77], v[34:35], v[0:1] op_sel_hi:[0,1,1]
	s_waitcnt vmcnt(16)
	v_pk_fma_f32 v[4:5], v[78:79], v[30:31], v[4:5] op_sel_hi:[0,1,1]
	v_pk_fma_f32 v[0:1], v[78:79], v[38:39], v[0:1] op_sel_hi:[0,1,1]
	v_add_co_u32_e64 v14, s[4:5], s14, v6
	v_add_co_u32_e32 v12, vcc, 0xfffd0000, v6
	s_nop 0
	v_addc_co_u32_e64 v15, s[4:5], -1, v7, s[4:5]
	v_add_co_u32_e64 v16, s[4:5], s15, v6
	global_load_dword v64, v[6:7], off
	s_nop 0
	v_addc_co_u32_e64 v17, s[4:5], -1, v7, s[4:5]
	v_add_co_u32_e64 v18, s[4:5], s16, v6
	v_addc_co_u32_e32 v13, vcc, -1, v7, vcc
	s_nop 0
	v_addc_co_u32_e64 v19, s[4:5], -1, v7, s[4:5]
	v_add_co_u32_e64 v20, s[4:5], s13, v6
	s_nop 1
	v_addc_co_u32_e64 v21, s[4:5], 0, v7, s[4:5]
	v_add_co_u32_e64 v22, s[4:5], s17, v6
	s_nop 1
	v_addc_co_u32_e64 v23, s[4:5], 0, v7, s[4:5]
	v_add_co_u32_e64 v24, s[4:5], s18, v6
	s_nop 1
	v_addc_co_u32_e64 v25, s[4:5], 0, v7, s[4:5]
	global_load_dword v66, v[14:15], off
	global_load_dword v68, v[16:17], off
	global_load_dword v70, v[12:13], off
	global_load_dword v72, v[18:19], off
	global_load_dword v74, v[20:21], off
	global_load_dword v76, v[22:23], off
	global_load_dword v78, v[24:25], off
	v_lshl_add_u64 v[6:7], v[6:7], 0, s[10:11]
	ds_read_b128 v[12:15], v11 offset:352
	ds_read_b128 v[16:19], v11 offset:864
	ds_read_b128 v[20:23], v11 offset:1376
	ds_read_b128 v[24:27], v11 offset:1888
	ds_read_b128 v[28:31], v11 offset:368
	ds_read_b128 v[32:35], v11 offset:880
	ds_read_b128 v[36:39], v11 offset:1392
	ds_read_b128 v[40:43], v11 offset:1904
	s_waitcnt lgkmcnt(6)
	v_mov_b32_e32 v60, v16
	v_mov_b32_e32 v61, v12
	s_waitcnt lgkmcnt(4)
	v_mov_b32_e32 v62, v24
	v_mov_b32_e32 v63, v20
	v_mov_b32_e32 v12, v17
	v_mov_b32_e32 v20, v25
	v_mov_b32_e32 v16, v18
	v_mov_b32_e32 v17, v14
	v_mov_b32_e32 v14, v19
	v_mov_b32_e32 v18, v26
	v_mov_b32_e32 v19, v22
	v_mov_b32_e32 v22, v27
	s_waitcnt lgkmcnt(2)
	v_mov_b32_e32 v24, v32
	v_mov_b32_e32 v25, v28
	s_waitcnt lgkmcnt(0)
	v_mov_b32_e32 v26, v40
	v_mov_b32_e32 v27, v36
	v_mov_b32_e32 v28, v33
	v_mov_b32_e32 v36, v41
	v_mov_b32_e32 v32, v34
	v_mov_b32_e32 v33, v30
	v_mov_b32_e32 v30, v35
	v_mov_b32_e32 v34, v42
	v_mov_b32_e32 v35, v38
	v_mov_b32_e32 v38, v43
	s_waitcnt vmcnt(20)
	v_pk_fma_f32 v[4:5], v[86:87], v[60:61], v[4:5] op_sel_hi:[0,1,1]
	v_pk_fma_f32 v[0:1], v[86:87], v[62:63], v[0:1] op_sel_hi:[0,1,1]
	v_pk_fma_f32 v[4:5], v[82:83], v[12:13], v[4:5] op_sel_hi:[0,1,1]
	v_pk_fma_f32 v[0:1], v[82:83], v[20:21], v[0:1] op_sel_hi:[0,1,1]
	v_pk_fma_f32 v[4:5], v[84:85], v[16:17], v[4:5] op_sel_hi:[0,1,1]
	v_pk_fma_f32 v[0:1], v[84:85], v[18:19], v[0:1] op_sel_hi:[0,1,1]
	s_waitcnt vmcnt(19)
	v_pk_fma_f32 v[4:5], v[88:89], v[14:15], v[4:5] op_sel_hi:[0,1,1]
	v_pk_fma_f32 v[0:1], v[88:89], v[22:23], v[0:1] op_sel_hi:[0,1,1]
	v_pk_fma_f32 v[4:5], v[80:81], v[24:25], v[4:5] op_sel_hi:[0,1,1]
	v_pk_fma_f32 v[0:1], v[80:81], v[26:27], v[0:1] op_sel_hi:[0,1,1]
	s_waitcnt vmcnt(18)
	v_pk_fma_f32 v[4:5], v[90:91], v[28:29], v[4:5] op_sel_hi:[0,1,1]
	v_pk_fma_f32 v[0:1], v[90:91], v[36:37], v[0:1] op_sel_hi:[0,1,1]
	s_waitcnt vmcnt(17)
	v_pk_fma_f32 v[4:5], v[92:93], v[32:33], v[4:5] op_sel_hi:[0,1,1]
	v_pk_fma_f32 v[0:1], v[92:93], v[34:35], v[0:1] op_sel_hi:[0,1,1]
	s_waitcnt vmcnt(16)
	v_pk_fma_f32 v[4:5], v[94:95], v[30:31], v[4:5] op_sel_hi:[0,1,1]
	v_pk_fma_f32 v[0:1], v[94:95], v[38:39], v[0:1] op_sel_hi:[0,1,1]
	v_add_co_u32_e64 v14, s[4:5], s14, v6
	v_add_co_u32_e32 v12, vcc, 0xfffd0000, v6
	s_nop 0
	v_addc_co_u32_e64 v15, s[4:5], -1, v7, s[4:5]
	v_add_co_u32_e64 v16, s[4:5], s15, v6
	global_load_dword v80, v[6:7], off
	s_nop 0
	v_addc_co_u32_e64 v17, s[4:5], -1, v7, s[4:5]
	v_add_co_u32_e64 v18, s[4:5], s16, v6
	v_addc_co_u32_e32 v13, vcc, -1, v7, vcc
	s_nop 0
	v_addc_co_u32_e64 v19, s[4:5], -1, v7, s[4:5]
	v_add_co_u32_e64 v20, s[4:5], s13, v6
	s_nop 1
	v_addc_co_u32_e64 v21, s[4:5], 0, v7, s[4:5]
	v_add_co_u32_e64 v22, s[4:5], s17, v6
	s_nop 1
	v_addc_co_u32_e64 v23, s[4:5], 0, v7, s[4:5]
	v_add_co_u32_e64 v24, s[4:5], s18, v6
	s_nop 1
	v_addc_co_u32_e64 v25, s[4:5], 0, v7, s[4:5]
	global_load_dword v82, v[14:15], off
	global_load_dword v84, v[16:17], off
	global_load_dword v86, v[12:13], off
	global_load_dword v88, v[18:19], off
	global_load_dword v90, v[20:21], off
	global_load_dword v92, v[22:23], off
	global_load_dword v94, v[24:25], off
	v_lshl_add_u64 v[6:7], v[6:7], 0, s[10:11]
	ds_read_b128 v[12:15], v11 offset:384
	ds_read_b128 v[16:19], v11 offset:896
	ds_read_b128 v[20:23], v11 offset:1408
	ds_read_b128 v[24:27], v11 offset:1920
	ds_read_b128 v[28:31], v11 offset:400
	ds_read_b128 v[32:35], v11 offset:912
	ds_read_b128 v[36:39], v11 offset:1424
	ds_read_b128 v[40:43], v11 offset:1936
	s_waitcnt lgkmcnt(6)
; DI void ada_partials(const P& p, LAS unsigned char* L) {
;     ...
; #pragma unroll 8
;         for (int k = 0; k < 128; ++k) { const float wv = w[(size_t)k * MODW]; a0 += condl[k] * wv; a1 += condl[128 + k] * wv; a2 += condl[256 + k] * wv; a3 += condl[384 + k] * wv; }
	v_mov_b32_e32 v60, v16
	v_mov_b32_e32 v61, v12
	s_waitcnt lgkmcnt(4)
	v_mov_b32_e32 v62, v24
	v_mov_b32_e32 v63, v20
	v_mov_b32_e32 v12, v17
	v_mov_b32_e32 v20, v25
	v_mov_b32_e32 v16, v18
	v_mov_b32_e32 v17, v14
	v_mov_b32_e32 v14, v19
	v_mov_b32_e32 v18, v26
	v_mov_b32_e32 v19, v22
	v_mov_b32_e32 v22, v27
	s_waitcnt lgkmcnt(2)
	v_mov_b32_e32 v24, v32
	v_mov_b32_e32 v25, v28
	s_waitcnt lgkmcnt(0)
	v_mov_b32_e32 v26, v40
	v_mov_b32_e32 v27, v36
	v_mov_b32_e32 v28, v33
	v_mov_b32_e32 v36, v41
	v_mov_b32_e32 v32, v34
	v_mov_b32_e32 v33, v30
	v_mov_b32_e32 v30, v35
	v_mov_b32_e32 v34, v42
	v_mov_b32_e32 v35, v38
	v_mov_b32_e32 v38, v43
	s_waitcnt vmcnt(20)
	v_pk_fma_f32 v[4:5], v[50:51], v[60:61], v[4:5] op_sel_hi:[0,1,1]
	v_pk_fma_f32 v[0:1], v[50:51], v[62:63], v[0:1] op_sel_hi:[0,1,1]
	v_pk_fma_f32 v[4:5], v[46:47], v[12:13], v[4:5] op_sel_hi:[0,1,1]
	v_pk_fma_f32 v[0:1], v[46:47], v[20:21], v[0:1] op_sel_hi:[0,1,1]
	v_pk_fma_f32 v[4:5], v[48:49], v[16:17], v[4:5] op_sel_hi:[0,1,1]
	v_pk_fma_f32 v[0:1], v[48:49], v[18:19], v[0:1] op_sel_hi:[0,1,1]
	s_waitcnt vmcnt(19)
	v_pk_fma_f32 v[4:5], v[52:53], v[14:15], v[4:5] op_sel_hi:[0,1,1]
	v_pk_fma_f32 v[0:1], v[52:53], v[22:23], v[0:1] op_sel_hi:[0,1,1]
	v_pk_fma_f32 v[4:5], v[44:45], v[24:25], v[4:5] op_sel_hi:[0,1,1]
	v_pk_fma_f32 v[0:1], v[44:45], v[26:27], v[0:1] op_sel_hi:[0,1,1]
	s_waitcnt vmcnt(18)
	v_pk_fma_f32 v[4:5], v[54:55], v[28:29], v[4:5] op_sel_hi:[0,1,1]
	v_pk_fma_f32 v[0:1], v[54:55], v[36:37], v[0:1] op_sel_hi:[0,1,1]
	s_waitcnt vmcnt(17)
	v_pk_fma_f32 v[4:5], v[56:57], v[32:33], v[4:5] op_sel_hi:[0,1,1]
	v_pk_fma_f32 v[0:1], v[56:57], v[34:35], v[0:1] op_sel_hi:[0,1,1]
	s_waitcnt vmcnt(16)
	v_pk_fma_f32 v[4:5], v[58:59], v[30:31], v[4:5] op_sel_hi:[0,1,1]
	v_pk_fma_f32 v[0:1], v[58:59], v[38:39], v[0:1] op_sel_hi:[0,1,1]
	v_add_co_u32_e64 v14, s[4:5], s14, v6
	v_add_co_u32_e32 v12, vcc, 0xfffd0000, v6
	s_nop 0
	v_addc_co_u32_e64 v15, s[4:5], -1, v7, s[4:5]
	v_add_co_u32_e64 v16, s[4:5], s15, v6
	global_load_dword v44, v[6:7], off
	s_nop 0
	v_addc_co_u32_e64 v17, s[4:5], -1, v7, s[4:5]
	v_add_co_u32_e64 v18, s[4:5], s16, v6
	v_addc_co_u32_e32 v13, vcc, -1, v7, vcc
	s_nop 0
	v_addc_co_u32_e64 v19, s[4:5], -1, v7, s[4:5]
	v_add_co_u32_e64 v20, s[4:5], s13, v6
	s_nop 1
	v_addc_co_u32_e64 v21, s[4:5], 0, v7, s[4:5]
	v_add_co_u32_e64 v22, s[4:5], s17, v6
	s_nop 1
	v_addc_co_u32_e64 v23, s[4:5], 0, v7, s[4:5]
	v_add_co_u32_e64 v24, s[4:5], s18, v6
	s_nop 1
	v_addc_co_u32_e64 v25, s[4:5], 0, v7, s[4:5]
	global_load_dword v46, v[14:15], off
	global_load_dword v48, v[16:17], off
	global_load_dword v50, v[12:13], off
	global_load_dword v52, v[18:19], off
	global_load_dword v54, v[20:21], off
	global_load_dword v56, v[22:23], off
	global_load_dword v58, v[24:25], off
	v_lshl_add_u64 v[6:7], v[6:7], 0, s[10:11]
	ds_read_b128 v[12:15], v11 offset:416
	ds_read_b128 v[16:19], v11 offset:928
	ds_read_b128 v[20:23], v11 offset:1440
	ds_read_b128 v[24:27], v11 offset:1952
	ds_read_b128 v[28:31], v11 offset:432
	ds_read_b128 v[32:35], v11 offset:944
	ds_read_b128 v[36:39], v11 offset:1456
	ds_read_b128 v[40:43], v11 offset:1968
	s_waitcnt lgkmcnt(6)
	v_mov_b32_e32 v60, v16
	v_mov_b32_e32 v61, v12
	s_waitcnt lgkmcnt(4)
	v_mov_b32_e32 v62, v24
	v_mov_b32_e32 v63, v20
	v_mov_b32_e32 v12, v17
	v_mov_b32_e32 v20, v25
	v_mov_b32_e32 v16, v18
	v_mov_b32_e32 v17, v14
	v_mov_b32_e32 v14, v19
	v_mov_b32_e32 v18, v26
	v_mov_b32_e32 v19, v22
	v_mov_b32_e32 v22, v27
	s_waitcnt lgkmcnt(2)
	v_mov_b32_e32 v24, v32
	v_mov_b32_e32 v25, v28
	s_waitcnt lgkmcnt(0)
	v_mov_b32_e32 v26, v40
	v_mov_b32_e32 v27, v36
	v_mov_b32_e32 v28, v33
	v_mov_b32_e32 v36, v41
	v_mov_b32_e32 v32, v34
	v_mov_b32_e32 v33, v30
	v_mov_b32_e32 v30, v35
	v_mov_b32_e32 v34, v42
	v_mov_b32_e32 v35, v38
	v_mov_b32_e32 v38, v43
	s_waitcnt vmcnt(20)
	v_pk_fma_f32 v[4:5], v[70:71], v[60:61], v[4:5] op_sel_hi:[0,1,1]
	v_pk_fma_f32 v[0:1], v[70:71], v[62:63], v[0:1] op_sel_hi:[0,1,1]
	v_pk_fma_f32 v[4:5], v[66:67], v[12:13], v[4:5] op_sel_hi:[0,1,1]
	v_pk_fma_f32 v[0:1], v[66:67], v[20:21], v[0:1] op_sel_hi:[0,1,1]
	v_pk_fma_f32 v[4:5], v[68:69], v[16:17], v[4:5] op_sel_hi:[0,1,1]
	v_pk_fma_f32 v[0:1], v[68:69], v[18:19], v[0:1] op_sel_hi:[0,1,1]
	s_waitcnt vmcnt(19)
	v_pk_fma_f32 v[4:5], v[72:73], v[14:15], v[4:5] op_sel_hi:[0,1,1]
	v_pk_fma_f32 v[0:1], v[72:73], v[22:23], v[0:1] op_sel_hi:[0,1,1]
	v_pk_fma_f32 v[4:5], v[64:65], v[24:25], v[4:5] op_sel_hi:[0,1,1]
	v_pk_fma_f32 v[0:1], v[64:65], v[26:27], v[0:1] op_sel_hi:[0,1,1]
	s_waitcnt vmcnt(18)
	v_pk_fma_f32 v[4:5], v[74:75], v[28:29], v[4:5] op_sel_hi:[0,1,1]
	v_pk_fma_f32 v[0:1], v[74:75], v[36:37], v[0:1] op_sel_hi:[0,1,1]
	s_waitcnt vmcnt(17)
	v_pk_fma_f32 v[4:5], v[76:77], v[32:33], v[4:5] op_sel_hi:[0,1,1]
	v_pk_fma_f32 v[0:1], v[76:77], v[34:35], v[0:1] op_sel_hi:[0,1,1]
	s_waitcnt vmcnt(16)
; DI void ada_partials(const P& p, LAS unsigned char* L) {
;     ...
; #pragma unroll 8
;         for (int k = 0; k < 128; ++k) { const float wv = w[(size_t)k * MODW]; a0 += condl[k] * wv; a1 += condl[128 + k] * wv; a2 += condl[256 + k] * wv; a3 += condl[384 + k] * wv; }
;         float* o = modp + ((size_t)(ks * 2 + l) * 4) * MODW + col;
;         o[0] = a0; o[MODW] = a1; o[2 * MODW] = a2; o[3 * MODW] = a3;
;     }
	v_pk_fma_f32 v[4:5], v[78:79], v[30:31], v[4:5] op_sel_hi:[0,1,1]
	v_pk_fma_f32 v[0:1], v[78:79], v[38:39], v[0:1] op_sel_hi:[0,1,1]
	ds_read_b128 v[12:15], v11 offset:448
	ds_read_b128 v[16:19], v11 offset:960
	ds_read_b128 v[20:23], v11 offset:1472
	ds_read_b128 v[24:27], v11 offset:1984
	ds_read_b128 v[28:31], v11 offset:464
	ds_read_b128 v[32:35], v11 offset:976
	ds_read_b128 v[36:39], v11 offset:1488
	ds_read_b128 v[40:43], v11 offset:2000
	s_waitcnt lgkmcnt(6)
	v_mov_b32_e32 v60, v16
	v_mov_b32_e32 v61, v12
	s_waitcnt lgkmcnt(4)
	v_mov_b32_e32 v62, v24
	v_mov_b32_e32 v63, v20
	v_mov_b32_e32 v12, v17
	v_mov_b32_e32 v20, v25
	v_mov_b32_e32 v16, v18
	v_mov_b32_e32 v17, v14
	v_mov_b32_e32 v14, v19
	v_mov_b32_e32 v18, v26
	v_mov_b32_e32 v19, v22
	v_mov_b32_e32 v22, v27
	s_waitcnt lgkmcnt(2)
	v_mov_b32_e32 v24, v32
	v_mov_b32_e32 v25, v28
	s_waitcnt lgkmcnt(0)
	v_mov_b32_e32 v26, v40
	v_mov_b32_e32 v27, v36
	v_mov_b32_e32 v28, v33
	v_mov_b32_e32 v36, v41
	v_mov_b32_e32 v32, v34
	v_mov_b32_e32 v33, v30
	v_mov_b32_e32 v30, v35
	v_mov_b32_e32 v34, v42
	v_mov_b32_e32 v35, v38
	v_mov_b32_e32 v38, v43
	s_waitcnt vmcnt(12)
	v_pk_fma_f32 v[4:5], v[86:87], v[60:61], v[4:5] op_sel_hi:[0,1,1]
	v_pk_fma_f32 v[0:1], v[86:87], v[62:63], v[0:1] op_sel_hi:[0,1,1]
	v_pk_fma_f32 v[4:5], v[82:83], v[12:13], v[4:5] op_sel_hi:[0,1,1]
	v_pk_fma_f32 v[0:1], v[82:83], v[20:21], v[0:1] op_sel_hi:[0,1,1]
	v_pk_fma_f32 v[4:5], v[84:85], v[16:17], v[4:5] op_sel_hi:[0,1,1]
	v_pk_fma_f32 v[0:1], v[84:85], v[18:19], v[0:1] op_sel_hi:[0,1,1]
	s_waitcnt vmcnt(11)
	v_pk_fma_f32 v[4:5], v[88:89], v[14:15], v[4:5] op_sel_hi:[0,1,1]
	v_pk_fma_f32 v[0:1], v[88:89], v[22:23], v[0:1] op_sel_hi:[0,1,1]
	v_pk_fma_f32 v[4:5], v[80:81], v[24:25], v[4:5] op_sel_hi:[0,1,1]
	v_pk_fma_f32 v[0:1], v[80:81], v[26:27], v[0:1] op_sel_hi:[0,1,1]
	s_waitcnt vmcnt(10)
	v_pk_fma_f32 v[4:5], v[90:91], v[28:29], v[4:5] op_sel_hi:[0,1,1]
	v_pk_fma_f32 v[0:1], v[90:91], v[36:37], v[0:1] op_sel_hi:[0,1,1]
	s_waitcnt vmcnt(9)
	v_pk_fma_f32 v[4:5], v[92:93], v[32:33], v[4:5] op_sel_hi:[0,1,1]
	v_pk_fma_f32 v[0:1], v[92:93], v[34:35], v[0:1] op_sel_hi:[0,1,1]
	s_waitcnt vmcnt(8)
	v_pk_fma_f32 v[4:5], v[94:95], v[30:31], v[4:5] op_sel_hi:[0,1,1]
	v_pk_fma_f32 v[0:1], v[94:95], v[38:39], v[0:1] op_sel_hi:[0,1,1]
	ds_read_b128 v[12:15], v11 offset:480
	ds_read_b128 v[16:19], v11 offset:992
	ds_read_b128 v[20:23], v11 offset:1504
	ds_read_b128 v[24:27], v11 offset:2016
	ds_read_b128 v[28:31], v11 offset:496
	ds_read_b128 v[32:35], v11 offset:1008
	ds_read_b128 v[36:39], v11 offset:1520
	ds_read_b128 v[40:43], v11 offset:2032
	s_waitcnt lgkmcnt(6)
	v_mov_b32_e32 v60, v16
	v_mov_b32_e32 v61, v12
	s_waitcnt lgkmcnt(4)
	v_mov_b32_e32 v62, v24
	v_mov_b32_e32 v63, v20
	v_mov_b32_e32 v12, v17
	v_mov_b32_e32 v20, v25
	v_mov_b32_e32 v16, v18
	v_mov_b32_e32 v17, v14
	v_mov_b32_e32 v14, v19
	v_mov_b32_e32 v18, v26
	v_mov_b32_e32 v19, v22
	v_mov_b32_e32 v22, v27
	s_waitcnt lgkmcnt(2)
	v_mov_b32_e32 v24, v32
	v_mov_b32_e32 v25, v28
	s_waitcnt lgkmcnt(0)
	v_mov_b32_e32 v26, v40
	v_mov_b32_e32 v27, v36
	v_mov_b32_e32 v28, v33
	v_mov_b32_e32 v36, v41
	v_mov_b32_e32 v32, v34
	v_mov_b32_e32 v33, v30
	v_mov_b32_e32 v30, v35
	v_mov_b32_e32 v34, v42
	v_mov_b32_e32 v35, v38
	v_mov_b32_e32 v38, v43
	s_waitcnt vmcnt(4)
	v_pk_fma_f32 v[4:5], v[50:51], v[60:61], v[4:5] op_sel_hi:[0,1,1]
	v_pk_fma_f32 v[0:1], v[50:51], v[62:63], v[0:1] op_sel_hi:[0,1,1]
	v_pk_fma_f32 v[4:5], v[46:47], v[12:13], v[4:5] op_sel_hi:[0,1,1]
	v_pk_fma_f32 v[0:1], v[46:47], v[20:21], v[0:1] op_sel_hi:[0,1,1]
	v_pk_fma_f32 v[4:5], v[48:49], v[16:17], v[4:5] op_sel_hi:[0,1,1]
	v_pk_fma_f32 v[0:1], v[48:49], v[18:19], v[0:1] op_sel_hi:[0,1,1]
	s_waitcnt vmcnt(3)
	v_pk_fma_f32 v[4:5], v[52:53], v[14:15], v[4:5] op_sel_hi:[0,1,1]
	v_pk_fma_f32 v[0:1], v[52:53], v[22:23], v[0:1] op_sel_hi:[0,1,1]
	v_pk_fma_f32 v[4:5], v[44:45], v[24:25], v[4:5] op_sel_hi:[0,1,1]
	v_pk_fma_f32 v[0:1], v[44:45], v[26:27], v[0:1] op_sel_hi:[0,1,1]
	s_waitcnt vmcnt(2)
	v_pk_fma_f32 v[4:5], v[54:55], v[28:29], v[4:5] op_sel_hi:[0,1,1]
	v_pk_fma_f32 v[0:1], v[54:55], v[36:37], v[0:1] op_sel_hi:[0,1,1]
	s_waitcnt vmcnt(1)
	v_pk_fma_f32 v[4:5], v[56:57], v[32:33], v[4:5] op_sel_hi:[0,1,1]
	v_pk_fma_f32 v[0:1], v[56:57], v[34:35], v[0:1] op_sel_hi:[0,1,1]
	s_waitcnt vmcnt(0)
	v_pk_fma_f32 v[4:5], v[58:59], v[30:31], v[4:5] op_sel_hi:[0,1,1]
	v_pk_fma_f32 v[0:1], v[58:59], v[38:39], v[0:1] op_sel_hi:[0,1,1]
	s_lshl_b32 s4, s21, 1
	s_add_i32 s4, s4, s20
	s_mul_hi_i32 s5, s4, 0x30000
	s_mul_i32 s4, s4, 0x30000
	s_add_u32 s4, s6, s4
	s_addc_u32 s5, s7, s5
	v_lshl_add_u64 v[2:3], v[2:3], 2, s[4:5]
	v_add_co_u32_e32 v6, vcc, 0xc000, v2
	global_store_dword v[2:3], v5, off
	s_nop 0
	v_addc_co_u32_e32 v7, vcc, 0, v3, vcc
	global_store_dword v[6:7], v4, off
	v_add_co_u32_e32 v4, vcc, 0x18000, v2
	s_add_i32 s19, s19, s86
	s_nop 0
	v_addc_co_u32_e32 v5, vcc, 0, v3, vcc
	v_add_co_u32_e32 v2, vcc, 0x24000, v2
	s_cmpk_gt_i32 s19, 0x2ff
	s_nop 0
	v_addc_co_u32_e32 v3, vcc, 0, v3, vcc
	global_store_dword v[4:5], v1, off
	global_store_dword v[2:3], v0, off
	s_cbranch_scc0 .LBB0_46

; DI unsigned pk2(float lo, float hi) { return pg8::cvt_pk_bf16(lo, hi); }
; DI void norm_rows(const float* X, const float* gain, const float* sh, const float* sc, bf16_t* H, int gw, int ngw, int lane) {
;     for (int m = gw; m < T_TOK; m += ngw) {
;         const int b = m >> 12;
;         const f32x4* xr = (const f32x4*)(X + (size_t)m * DM) + lane;
;         f32x4 v[8]; float s = 0.f;
; #pragma unroll
;         for (int j = 0; j < 8; ++j) { v[j] = xr[64 * j]; s += (v[j].x * v[j].x + v[j].y * v[j].y) + (v[j].z * v[j].z + v[j].w * v[j].w); }
;         const float rstd = rsqrtf(wave_sum(s) * (1.f / DM) + EPS);
;         const f32x4* gp = (const f32x4*)gain + lane; const f32x4* scp = (const f32x4*)(sc + (size_t)b * MODW) + lane; const f32x4* shp = (const f32x4*)(sh + (size_t)b * MODW) + lane;
;         u32x2* o = (u32x2*)(H + (size_t)m * DM) + lane;
; #pragma unroll
;         for (int j = 0; j < 8; ++j) { const f32x4 r = v[j] * rstd * gp[64 * j] * (scp[64 * j] + 1.0f) + shp[64 * j]; u32x2 w; w.x = pk2(r.x, r.y); w.y = pk2(r.z, r.w); o[64 * j] = w; }
.LBB0_156:
	s_or_b64 exec, exec, s[4:5]
	s_mov_b64 s[6:7], s[0:1]
	s_waitcnt lgkmcnt(0)
	v_mov_b32_e32 v0, v220
	s_barrier
	v_readlane_b32 s4, v253, 2
	v_readfirstlane_b32 s3, v0
	s_ashr_i32 s3, s3, 6
	s_add_i32 s4, s3, s4
	s_cmpk_gt_i32 s4, 0x3fff
	v_mbcnt_lo_u32_b32 v144, -1, 0
	s_cbranch_scc1 .LBB0_159
	v_and_b32_e32 v4, 63, v0
	v_mbcnt_hi_u32_b32 v0, -1, v144
	v_and_b32_e32 v1, 64, v0
	v_add_u32_e32 v1, 64, v1
	v_xor_b32_e32 v2, 1, v0
	v_cmp_lt_i32_e32 vcc, v2, v1
	s_load_dwordx2 s[8:9], s[6:7], 0x0
	s_load_dwordx2 s[10:11], s[6:7], 0x20
	s_load_dwordx2 s[12:13], s[6:7], 0xb0
	v_cndmask_b32_e32 v2, v0, v2, vcc
	v_lshlrev_b32_e32 v50, 2, v2
	v_xor_b32_e32 v2, 2, v0
	v_cmp_lt_i32_e32 vcc, v2, v1
	s_ashr_i32 s5, s4, 31
	s_mov_b64 s[6:7], 0x602000
	v_cndmask_b32_e32 v2, v0, v2, vcc
	v_lshlrev_b32_e32 v51, 2, v2
	v_xor_b32_e32 v2, 4, v0
	v_cmp_lt_i32_e32 vcc, v2, v1
	v_mov_b32_e32 v56, 0x358637bd
	s_mov_b32 s3, 0x800000
	v_cndmask_b32_e32 v2, v0, v2, vcc
	v_lshlrev_b32_e32 v52, 2, v2
	v_xor_b32_e32 v2, 8, v0
	v_cmp_lt_i32_e32 vcc, v2, v1
	v_mov_b32_e32 v57, 0xc000
	s_nop 0
	v_cndmask_b32_e32 v2, v0, v2, vcc
	v_lshlrev_b32_e32 v53, 2, v2
	v_xor_b32_e32 v2, 16, v0
	v_cmp_lt_i32_e32 vcc, v2, v1
	s_nop 1
	v_cndmask_b32_e32 v2, v0, v2, vcc
	v_lshlrev_b32_e32 v54, 2, v2
	v_xor_b32_e32 v2, 32, v0
	v_cmp_lt_i32_e32 vcc, v2, v1
	v_mov_b32_e32 v1, 0
	s_nop 0
	v_cndmask_b32_e32 v0, v0, v2, vcc
	v_lshlrev_b32_e32 v55, 2, v0
	v_lshlrev_b32_e32 v0, 4, v4
	s_waitcnt lgkmcnt(0)
	v_lshl_add_u64 v[32:33], s[10:11], 0, v[0:1]
	s_mov_b64 s[10:11], 0x1400
	v_lshl_add_u64 v[40:41], v[32:33], 0, s[10:11]
	s_mov_b64 s[10:11], 0x1800
	v_lshl_add_u64 v[42:43], v[32:33], 0, s[10:11]
	s_mov_b64 s[10:11], 0x1c00
	v_lshl_add_u64 v[44:45], v[32:33], 0, s[10:11]
	s_lshl_b64 s[10:11], s[4:5], 13
	v_lshl_add_u64 v[2:3], s[12:13], 0, v[0:1]
	s_add_u32 s8, s8, s10
	v_lshl_add_u64 v[34:35], v[2:3], 0, s[6:7]
	s_mov_b64 s[6:7], 0x600000
	s_addc_u32 s9, s9, s11
	v_lshl_add_u64 v[36:37], v[2:3], 0, s[6:7]
	s_mov_b64 s[6:7], 0x1000
	v_lshl_add_u64 v[2:3], s[8:9], 0, v[0:1]
	s_ashr_i32 s85, s84, 31
	v_lshl_add_u64 v[38:39], v[32:33], 0, s[6:7]
	v_lshl_add_u64 v[46:47], v[2:3], 0, s[6:7]
	s_lshl_b64 s[6:7], s[84:85], 13
	s_lshl_b64 s[8:9], s[4:5], 12
	s_add_u32 s8, s12, s8
	v_lshlrev_b32_e32 v0, 3, v4
	s_addc_u32 s9, s13, s9
	v_lshl_add_u64 v[0:1], s[8:9], 0, v[0:1]
	s_mov_b64 s[8:9], 0x7600000
	v_lshl_add_u64 v[48:49], v[0:1], 0, s[8:9]
	s_lshl_b64 s[8:9], s[84:85], 12
	s_movk_i32 s5, 0x1000
	s_mov_b64 s[98:99], 0x1000
.LBB0_158:
	global_load_dwordx4 v[28:31], v[46:47], off offset:-4096
	global_load_dwordx4 v[24:27], v[46:47], off offset:-3072
	global_load_dwordx4 v[20:23], v[46:47], off offset:-2048
	global_load_dwordx4 v[4:7], v[46:47], off offset:1024
	global_load_dwordx4 v[12:15], v[46:47], off offset:-1024
	global_load_dwordx4 v[16:19], v[46:47], off
	global_load_dwordx4 v[8:11], v[46:47], off offset:2048
	global_load_dwordx4 v[0:3], v[46:47], off offset:3072
	global_load_dwordx4 v[58:61], v[32:33], off
	s_ashr_i32 s12, s4, 12
	v_mad_i64_i32 v[70:71], s[10:11], s12, v57, v[34:35]
	v_mad_i64_i32 v[72:73], s[10:11], s12, v57, v[36:37]
	global_load_dwordx4 v[62:65], v[70:71], off
	global_load_dwordx4 v[66:69], v[72:73], off
	v_lshl_add_u64 v[108:109], v[70:71], 0, s[98:99]
	v_lshl_add_u64 v[110:111], v[72:73], 0, s[98:99]
	global_load_dwordx4 v[112:115], v[32:33], off offset:1024
	global_load_dwordx4 v[116:119], v[70:71], off offset:1024
	global_load_dwordx4 v[120:123], v[72:73], off offset:1024
	global_load_dwordx4 v[124:127], v[32:33], off offset:2048
	global_load_dwordx4 v[128:131], v[70:71], off offset:2048
	global_load_dwordx4 v[132:135], v[72:73], off offset:2048
	global_load_dwordx4 v[136:139], v[32:33], off offset:3072
	global_load_dwordx4 v[140:143], v[70:71], off offset:3072
	global_load_dwordx4 v[148:151], v[72:73], off offset:3072
	global_load_dwordx4 v[152:155], v[38:39], off
	global_load_dwordx4 v[156:159], v[108:109], off
	global_load_dwordx4 v[160:163], v[110:111], off
	global_load_dwordx4 v[164:167], v[40:41], off
	global_load_dwordx4 v[168:171], v[108:109], off offset:1024
	global_load_dwordx4 v[172:175], v[110:111], off offset:1024
	global_load_dwordx4 v[176:179], v[42:43], off
	global_load_dwordx4 v[180:183], v[108:109], off offset:2048
	global_load_dwordx4 v[184:187], v[110:111], off offset:2048
	global_load_dwordx4 v[188:191], v[44:45], off
	global_load_dwordx4 v[192:195], v[108:109], off offset:3072
	global_load_dwordx4 v[196:199], v[110:111], off offset:3072
	s_add_i32 s4, s4, s84
	v_lshl_add_u64 v[46:47], v[46:47], 0, s[6:7]
	s_cmpk_lt_i32 s4, 0x4000
	s_waitcnt vmcnt(31)
	v_mov_b32_e32 v76, v29
	s_waitcnt vmcnt(30)
	v_mov_b32_e32 v77, v25
	s_waitcnt vmcnt(29)
	v_pk_mul_f32 v[78:79], v[22:23], v[22:23]
	v_pk_mul_f32 v[80:81], v[20:21], v[20:21]
	s_waitcnt vmcnt(28)
	v_pk_mul_f32 v[82:83], v[6:7], v[6:7]
	v_pk_mul_f32 v[84:85], v[4:5], v[4:5]
	v_mov_b32_e32 v88, v31
	v_mov_b32_e32 v89, v27
	v_mov_b32_e32 v74, v28
	v_mov_b32_e32 v75, v24
	v_mov_b32_e32 v86, v30
	v_mov_b32_e32 v87, v26
	v_pk_mov_b32 v[98:99], v[80:81], v[78:79] op_sel:[1,0]
	v_mov_b32_e32 v81, v79
	v_pk_mov_b32 v[78:79], v[84:85], v[82:83] op_sel:[1,0]
	v_mov_b32_e32 v85, v83
	v_pk_mul_f32 v[76:77], v[76:77], v[76:77]
	v_pk_mul_f32 v[82:83], v[88:89], v[88:89]
	v_pk_fma_f32 v[74:75], v[74:75], v[74:75], v[76:77]
	v_pk_fma_f32 v[76:77], v[86:87], v[86:87], v[82:83]
	s_waitcnt vmcnt(27)
	v_mul_f32_e32 v90, v13, v13
	v_mul_f32_e32 v92, v15, v15
	v_pk_add_f32 v[80:81], v[98:99], v[80:81]
	v_pk_add_f32 v[74:75], v[74:75], v[76:77]
	s_waitcnt vmcnt(26)
; DI unsigned pk2(float lo, float hi) { return pg8::cvt_pk_bf16(lo, hi); }
; DI float wave_sum(float v) {
; #pragma unroll
;     for (int o = 1; o < 64; o <<= 1) v += __shfl_xor(v, o);
;     return v;
; }
; DI void norm_rows(const float* X, const float* gain, const float* sh, const float* sc, bf16_t* H, int gw, int ngw, int lane) {
;     ...
;         for (int j = 0; j < 8; ++j) { v[j] = xr[64 * j]; s += (v[j].x * v[j].x + v[j].y * v[j].y) + (v[j].z * v[j].z + v[j].w * v[j].w); }
;         const float rstd = rsqrtf(wave_sum(s) * (1.f / DM) + EPS);
;         const f32x4* gp = (const f32x4*)gain + lane; const f32x4* scp = (const f32x4*)(sc + (size_t)b * MODW) + lane; const f32x4* shp = (const f32x4*)(sh + (size_t)b * MODW) + lane;
;         u32x2* o = (u32x2*)(H + (size_t)m * DM) + lane;
; #pragma unroll
;         for (int j = 0; j < 8; ++j) { const f32x4 r = v[j] * rstd * gp[64 * j] * (scp[64 * j] + 1.0f) + shp[64 * j]; u32x2 w; w.x = pk2(r.x, r.y); w.y = pk2(r.z, r.w); o[64 * j] = w; }
	v_mul_f32_e32 v97, v18, v18
	v_mul_f32_e32 v100, v19, v19
	v_mul_f32_e32 v103, v17, v17
	v_mul_f32_e32 v104, v16, v16
	v_pk_fma_f32 v[88:89], v[12:13], v[12:13], v[90:91] op_sel_hi:[1,1,0]
	v_pk_fma_f32 v[90:91], v[14:15], v[14:15], v[92:93] op_sel_hi:[1,1,0]
	v_pk_add_f32 v[80:81], v[80:81], v[80:81] op_sel:[0,1] op_sel_hi:[1,0]
	v_pk_add_f32 v[74:75], v[74:75], v[74:75] op_sel:[0,1] op_sel_hi:[1,0]
	v_mov_b32_e32 v89, v97
	v_mov_b32_e32 v91, v100
	v_mov_b32_e32 v81, v103
	v_mov_b32_e32 v75, v104
	v_pk_add_f32 v[76:77], v[88:89], v[90:91]
	v_pk_add_f32 v[74:75], v[74:75], v[80:81]
	s_waitcnt vmcnt(25)
	v_mul_f32_e32 v94, v9, v9
	v_mul_f32_e32 v96, v11, v11
	v_pk_add_f32 v[78:79], v[78:79], v[84:85]
	v_pk_add_f32 v[74:75], v[74:75], v[76:77]
	s_waitcnt vmcnt(24)
	v_mul_f32_e32 v101, v2, v2
	v_mul_f32_e32 v102, v3, v3
	v_mul_f32_e32 v105, v1, v1
	v_mul_f32_e32 v106, v0, v0
	v_pk_fma_f32 v[92:93], v[8:9], v[8:9], v[94:95] op_sel_hi:[1,1,0]
	v_pk_fma_f32 v[94:95], v[10:11], v[10:11], v[96:97] op_sel_hi:[1,1,0]
	v_pk_add_f32 v[78:79], v[78:79], v[78:79] op_sel:[0,1] op_sel_hi:[1,0]
	v_pk_add_f32 v[74:75], v[74:75], v[74:75] op_sel:[0,1] op_sel_hi:[1,0]
	v_mov_b32_e32 v93, v101
	v_mov_b32_e32 v95, v102
	v_mov_b32_e32 v79, v105
	v_mov_b32_e32 v75, v106
	v_pk_add_f32 v[82:83], v[92:93], v[94:95]
	v_pk_add_f32 v[74:75], v[74:75], v[78:79]
	s_waitcnt vmcnt(22)
	v_pk_add_f32 v[64:65], v[64:65], 1.0 op_sel_hi:[1,0]
	v_pk_add_f32 v[74:75], v[74:75], v[82:83]
	v_pk_add_f32 v[62:63], v[62:63], 1.0 op_sel_hi:[1,0]
	v_add_f32_e32 v74, v74, v75
	ds_bpermute_b32 v75, v50, v74
	s_waitcnt lgkmcnt(0)
	v_add_f32_e32 v74, v74, v75
	ds_bpermute_b32 v75, v51, v74
	s_waitcnt lgkmcnt(0)
	v_add_f32_e32 v74, v74, v75
	ds_bpermute_b32 v75, v52, v74
	s_waitcnt lgkmcnt(0)
	v_add_f32_e32 v74, v74, v75
	ds_bpermute_b32 v75, v53, v74
	s_waitcnt lgkmcnt(0)
	v_add_f32_e32 v74, v74, v75
	ds_bpermute_b32 v75, v54, v74
	s_waitcnt lgkmcnt(0)
	v_add_f32_e32 v74, v74, v75
	ds_bpermute_b32 v75, v55, v74
	s_waitcnt lgkmcnt(0)
	v_add_f32_e32 v74, v74, v75
	v_fmamk_f32 v74, v74, 0x3a000000, v56
	v_mul_f32_e32 v75, 0x4b800000, v74
	v_cmp_gt_f32_e32 vcc, s3, v74
	s_nop 1
	v_cndmask_b32_e32 v74, v74, v75, vcc
	v_rsq_f32_e32 v74, v74
	s_nop 0
	v_mul_f32_e32 v75, 0x45800000, v74
	v_cndmask_b32_e32 v74, v74, v75, vcc
	v_pk_mul_f32 v[30:31], v[30:31], v[74:75] op_sel_hi:[1,0]
	v_pk_mul_f32 v[28:29], v[28:29], v[74:75] op_sel_hi:[1,0]
	v_pk_mul_f32 v[30:31], v[60:61], v[30:31]
	v_pk_mul_f32 v[28:29], v[58:59], v[28:29]
	s_waitcnt vmcnt(21)
	v_pk_fma_f32 v[30:31], v[64:65], v[30:31], v[68:69]
	v_pk_fma_f32 v[28:29], v[62:63], v[28:29], v[66:67]
	v_pk_mul_f32 v[26:27], v[26:27], v[74:75] op_sel_hi:[1,0]
	v_cvt_pk_bf16_f32 v28, v28, v29
	v_cvt_pk_bf16_f32 v29, v30, v31
	global_store_dwordx2 v[48:49], v[28:29], off
	v_pk_mul_f32 v[24:25], v[24:25], v[74:75] op_sel_hi:[1,0]
	v_pk_mul_f32 v[22:23], v[22:23], v[74:75] op_sel_hi:[1,0]
	v_pk_mul_f32 v[20:21], v[20:21], v[74:75] op_sel_hi:[1,0]
	v_pk_mul_f32 v[14:15], v[14:15], v[74:75] op_sel_hi:[1,0]
	v_pk_mul_f32 v[12:13], v[12:13], v[74:75] op_sel_hi:[1,0]
	v_pk_mul_f32 v[18:19], v[18:19], v[74:75] op_sel_hi:[1,0]
	v_pk_mul_f32 v[16:17], v[16:17], v[74:75] op_sel_hi:[1,0]
	v_pk_mul_f32 v[6:7], v[6:7], v[74:75] op_sel_hi:[1,0]
	v_pk_mul_f32 v[4:5], v[4:5], v[74:75] op_sel_hi:[1,0]
	v_pk_mul_f32 v[10:11], v[10:11], v[74:75] op_sel_hi:[1,0]
	v_pk_mul_f32 v[8:9], v[8:9], v[74:75] op_sel_hi:[1,0]
	v_pk_mul_f32 v[2:3], v[2:3], v[74:75] op_sel_hi:[1,0]
	v_pk_mul_f32 v[0:1], v[0:1], v[74:75] op_sel_hi:[1,0]
	s_waitcnt vmcnt(20)
; DI unsigned pk2(float lo, float hi) { return pg8::cvt_pk_bf16(lo, hi); }
; DI void norm_rows(const float* X, const float* gain, const float* sh, const float* sc, bf16_t* H, int gw, int ngw, int lane) {
;     ...
; #pragma unroll
;         for (int j = 0; j < 8; ++j) { const f32x4 r = v[j] * rstd * gp[64 * j] * (scp[64 * j] + 1.0f) + shp[64 * j]; u32x2 w; w.x = pk2(r.x, r.y); w.y = pk2(r.z, r.w); o[64 * j] = w; }
	v_pk_mul_f32 v[24:25], v[112:113], v[24:25]
	v_pk_mul_f32 v[26:27], v[114:115], v[26:27]
	s_waitcnt vmcnt(19)
	v_pk_add_f32 v[28:29], v[118:119], 1.0 op_sel_hi:[1,0]
	v_pk_add_f32 v[30:31], v[116:117], 1.0 op_sel_hi:[1,0]
	s_waitcnt vmcnt(18)
	v_pk_fma_f32 v[26:27], v[28:29], v[26:27], v[122:123]
	v_pk_fma_f32 v[24:25], v[30:31], v[24:25], v[120:121]
	s_nop 0
	v_cvt_pk_bf16_f32 v24, v24, v25
	v_cvt_pk_bf16_f32 v25, v26, v27
	global_store_dwordx2 v[48:49], v[24:25], off offset:512
	s_waitcnt vmcnt(17)
	v_pk_mul_f32 v[20:21], v[124:125], v[20:21]
	v_pk_mul_f32 v[22:23], v[126:127], v[22:23]
	s_waitcnt vmcnt(16)
	v_pk_add_f32 v[24:25], v[130:131], 1.0 op_sel_hi:[1,0]
	v_pk_add_f32 v[26:27], v[128:129], 1.0 op_sel_hi:[1,0]
	s_waitcnt vmcnt(15)
	v_pk_fma_f32 v[22:23], v[24:25], v[22:23], v[134:135]
	v_pk_fma_f32 v[20:21], v[26:27], v[20:21], v[132:133]
	v_add_co_u32_e32 v58, vcc, s5, v70
	v_cvt_pk_bf16_f32 v20, v20, v21
	v_cvt_pk_bf16_f32 v21, v22, v23
	global_store_dwordx2 v[48:49], v[20:21], off offset:1024
	v_addc_co_u32_e32 v59, vcc, 0, v71, vcc
	v_add_co_u32_e32 v60, vcc, s5, v72
	s_waitcnt vmcnt(14)
	v_pk_mul_f32 v[12:13], v[136:137], v[12:13]
	v_pk_mul_f32 v[14:15], v[138:139], v[14:15]
	s_waitcnt vmcnt(13)
	v_pk_add_f32 v[20:21], v[142:143], 1.0 op_sel_hi:[1,0]
	v_pk_add_f32 v[22:23], v[140:141], 1.0 op_sel_hi:[1,0]
	s_waitcnt vmcnt(12)
	v_pk_fma_f32 v[14:15], v[20:21], v[14:15], v[150:151]
	v_pk_fma_f32 v[12:13], v[22:23], v[12:13], v[148:149]
	v_addc_co_u32_e32 v61, vcc, 0, v73, vcc
	v_cvt_pk_bf16_f32 v12, v12, v13
	v_cvt_pk_bf16_f32 v13, v14, v15
	global_store_dwordx2 v[48:49], v[12:13], off offset:1536
	s_waitcnt vmcnt(11)
	v_pk_mul_f32 v[12:13], v[16:17], v[152:153]
	v_pk_mul_f32 v[14:15], v[18:19], v[154:155]
	s_waitcnt vmcnt(10)
	v_pk_add_f32 v[16:17], v[158:159], 1.0 op_sel_hi:[1,0]
	v_pk_add_f32 v[18:19], v[156:157], 1.0 op_sel_hi:[1,0]
	s_waitcnt vmcnt(9)
	v_pk_fma_f32 v[14:15], v[14:15], v[16:17], v[162:163]
	v_pk_fma_f32 v[12:13], v[12:13], v[18:19], v[160:161]
	s_nop 0
	v_cvt_pk_bf16_f32 v12, v12, v13
	v_cvt_pk_bf16_f32 v13, v14, v15
	global_store_dwordx2 v[48:49], v[12:13], off offset:2048
	s_waitcnt vmcnt(8)
	v_pk_mul_f32 v[4:5], v[4:5], v[164:165]
	v_pk_mul_f32 v[6:7], v[6:7], v[166:167]
	s_waitcnt vmcnt(7)
	v_pk_add_f32 v[12:13], v[170:171], 1.0 op_sel_hi:[1,0]
	v_pk_add_f32 v[14:15], v[168:169], 1.0 op_sel_hi:[1,0]
	s_waitcnt vmcnt(6)
	v_pk_fma_f32 v[6:7], v[6:7], v[12:13], v[174:175]
	v_pk_fma_f32 v[4:5], v[4:5], v[14:15], v[172:173]
	s_nop 0
	v_cvt_pk_bf16_f32 v4, v4, v5
	v_cvt_pk_bf16_f32 v5, v6, v7
	global_store_dwordx2 v[48:49], v[4:5], off offset:2560
	s_waitcnt vmcnt(5)
	v_pk_mul_f32 v[4:5], v[8:9], v[176:177]
	v_pk_mul_f32 v[6:7], v[10:11], v[178:179]
	s_waitcnt vmcnt(4)
	v_pk_add_f32 v[8:9], v[182:183], 1.0 op_sel_hi:[1,0]
	v_pk_add_f32 v[10:11], v[180:181], 1.0 op_sel_hi:[1,0]
	s_waitcnt vmcnt(3)
	v_pk_fma_f32 v[6:7], v[6:7], v[8:9], v[186:187]
	v_pk_fma_f32 v[4:5], v[4:5], v[10:11], v[184:185]
	s_nop 0
	v_cvt_pk_bf16_f32 v4, v4, v5
	v_cvt_pk_bf16_f32 v5, v6, v7
	global_store_dwordx2 v[48:49], v[4:5], off offset:3072
	s_waitcnt vmcnt(2)
	v_pk_mul_f32 v[0:1], v[0:1], v[188:189]
	v_pk_mul_f32 v[2:3], v[2:3], v[190:191]
	s_waitcnt vmcnt(1)
	v_pk_add_f32 v[4:5], v[194:195], 1.0 op_sel_hi:[1,0]
	v_pk_add_f32 v[6:7], v[192:193], 1.0 op_sel_hi:[1,0]
	s_waitcnt vmcnt(0)
	v_pk_fma_f32 v[2:3], v[2:3], v[4:5], v[198:199]
	v_pk_fma_f32 v[0:1], v[0:1], v[6:7], v[196:197]
	s_nop 0
	v_cvt_pk_bf16_f32 v0, v0, v1
	v_cvt_pk_bf16_f32 v1, v2, v3
	global_store_dwordx2 v[48:49], v[0:1], off offset:3584
	v_lshl_add_u64 v[48:49], v[48:49], 0, s[8:9]
	s_cbranch_scc1 .LBB0_158
